# attnA: spurious mid-loop vmcnt0 removed, K-fragment ds_reads batched with counted lgkmcnt, cross-half max via permlane32_swap
# speedup vs baseline: 1.0062x; 1.0062x over previous
.LBB0_182:
	v_fma_f32 v80, v80, s3, -v197
	v_exp_f32_e32 v80, v80
	v_fma_f32 v81, v81, s3, -v197
	v_fma_f32 v82, v82, s3, -v197
	v_exp_f32_e32 v81, v81
	v_exp_f32_e32 v82, v82
	v_fma_f32 v83, v83, s3, -v197
	v_exp_f32_e32 v83, v83
	v_fma_f32 v84, v84, s3, -v197
	v_add_f32_e32 v142, 0, v80
	v_exp_f32_e32 v143, v84
	v_fma_f32 v85, v85, s3, -v197
	v_add_f32_e32 v84, v81, v142
	v_exp_f32_e32 v142, v85
	v_fma_f32 v85, v86, s3, -v197
	v_add_f32_e32 v84, v82, v84
	v_exp_f32_e32 v144, v85
	v_fma_f32 v85, v87, s3, -v197
	v_add_f32_e32 v84, v83, v84
	v_exp_f32_e32 v145, v85
	v_fma_f32 v85, v88, s3, -v197
	v_add_f32_e32 v84, v143, v84
	v_exp_f32_e32 v198, v85
	v_add_f32_e32 v84, v142, v84
	v_add_f32_e32 v84, v144, v84
	v_add_f32_e32 v84, v145, v84
	v_add_f32_e32 v88, v198, v84
	v_fma_f32 v84, v89, s3, -v197
	v_exp_f32_e32 v199, v84
	v_fma_f32 v84, v90, s3, -v197
	v_add_u32_e32 v201, v173, v168
	v_exp_f32_e32 v200, v84
	ds_read_b64_tr_b16 v[84:85], v201 offset:32768
	ds_read_b64_tr_b16 v[86:87], v201 offset:34816
	v_add_u32_e32 v202, v173, v169
	v_cvt_pk_bf16_f32 v80, v80, v81
	v_cvt_pk_bf16_f32 v81, v82, v83
	v_cvt_pk_bf16_f32 v82, v143, v142
	v_cvt_pk_bf16_f32 v83, v144, v145
	ds_read_b64_tr_b16 v[142:143], v202 offset:32768
	ds_read_b64_tr_b16 v[144:145], v202 offset:34816
	ds_read_b64_tr_b16 v[146:147], v201 offset:36864
	ds_read_b64_tr_b16 v[148:149], v201 offset:38912
	s_waitcnt lgkmcnt(4)
	v_mfma_f32_32x32x16_bf16 v[48:63], v[84:87], v[80:83], v[48:63]
	v_add_f32_e32 v84, v199, v88
	v_add_u32_e32 v204, v173, v170
	v_add_f32_e32 v203, v200, v84
	ds_read_b64_tr_b16 v[84:85], v204 offset:32768
	ds_read_b64_tr_b16 v[86:87], v204 offset:34816
	ds_read_b64_tr_b16 v[150:151], v202 offset:36864
	ds_read_b64_tr_b16 v[152:153], v202 offset:38912
	v_fma_f32 v88, v91, s3, -v197
	v_add_u32_e32 v206, v173, v171
	v_exp_f32_e32 v205, v88
	s_waitcnt lgkmcnt(6)
	v_mfma_f32_32x32x16_bf16 v[32:47], v[142:145], v[80:83], v[32:47]
	ds_read_b64_tr_b16 v[88:89], v206 offset:32768
	ds_read_b64_tr_b16 v[90:91], v206 offset:34816
	ds_read_b64_tr_b16 v[142:143], v204 offset:36864
	ds_read_b64_tr_b16 v[144:145], v204 offset:38912
	v_fma_f32 v94, v94, s3, -v197
	v_exp_f32_e32 v94, v94
	v_fma_f32 v64, v64, s3, -v197
	v_fma_f32 v78, v78, s3, -v197
	s_waitcnt lgkmcnt(6)
	v_mfma_f32_32x32x16_bf16 v[16:31], v[84:87], v[80:83], v[16:31]
	v_fma_f32 v84, v92, s3, -v197
	v_exp_f32_e32 v92, v84
	v_fma_f32 v84, v93, s3, -v197
	v_exp_f32_e32 v93, v84
	ds_read_b64_tr_b16 v[84:85], v206 offset:36864
	ds_read_b64_tr_b16 v[86:87], v206 offset:38912
	s_waitcnt lgkmcnt(4)
	v_mfma_f32_32x32x16_bf16 v[0:15], v[88:91], v[80:83], v[0:15]
	v_fma_f32 v80, v95, s3, -v197
	v_exp_f32_e32 v95, v80
	v_cvt_pk_bf16_f32 v80, v198, v199
	v_cvt_pk_bf16_f32 v81, v200, v205
	v_cvt_pk_bf16_f32 v82, v92, v93
	v_cvt_pk_bf16_f32 v83, v94, v95
	s_nop 1
	v_mfma_f32_32x32x16_bf16 v[48:63], v[146:149], v[80:83], v[48:63]
	v_exp_f32_e32 v146, v64
	v_fma_f32 v64, v65, s3, -v197
	v_exp_f32_e32 v147, v64
	v_fma_f32 v64, v66, s3, -v197
	v_exp_f32_e32 v148, v64
	v_fma_f32 v64, v67, s3, -v197
	v_exp_f32_e32 v149, v64
	v_fma_f32 v64, v68, s3, -v197
	v_mfma_f32_32x32x16_bf16 v[32:47], v[150:153], v[80:83], v[32:47]
	v_exp_f32_e32 v150, v64
	v_fma_f32 v64, v69, s3, -v197
	v_exp_f32_e32 v151, v64
	v_fma_f32 v64, v70, s3, -v197
	v_exp_f32_e32 v152, v64
	v_fma_f32 v64, v71, s3, -v197
	ds_read_b64_tr_b16 v[68:69], v201 offset:40960
	ds_read_b64_tr_b16 v[70:71], v201 offset:43008
	s_waitcnt lgkmcnt(4)
	v_mfma_f32_32x32x16_bf16 v[16:31], v[142:145], v[80:83], v[16:31]
	v_exp_f32_e32 v142, v64
	v_fma_f32 v64, v72, s3, -v197
	v_exp_f32_e32 v143, v64
	v_cvt_pk_bf16_f32 v64, v146, v147
	v_cvt_pk_bf16_f32 v65, v148, v149
	v_cvt_pk_bf16_f32 v66, v150, v151
	v_cvt_pk_bf16_f32 v67, v152, v142
	s_waitcnt lgkmcnt(2)
	v_mfma_f32_32x32x16_bf16 v[0:15], v[84:87], v[80:83], v[0:15]
	ds_read_b64_tr_b16 v[80:81], v202 offset:40960
	ds_read_b64_tr_b16 v[82:83], v202 offset:43008
	ds_read_b64_tr_b16 v[84:85], v201 offset:45056
	ds_read_b64_tr_b16 v[86:87], v201 offset:47104
	v_fma_f32 v72, v74, s3, -v197
	v_exp_f32_e32 v145, v72
	v_fma_f32 v72, v75, s3, -v197
	v_exp_f32_e32 v153, v72
	s_waitcnt lgkmcnt(4)
	v_mfma_f32_32x32x16_bf16 v[48:63], v[68:71], v[64:67], v[48:63]
	v_fma_f32 v68, v73, s3, -v197
	v_exp_f32_e32 v144, v68
	ds_read_b64_tr_b16 v[68:69], v204 offset:40960
	ds_read_b64_tr_b16 v[70:71], v204 offset:43008
	ds_read_b64_tr_b16 v[88:89], v202 offset:45056
	ds_read_b64_tr_b16 v[90:91], v202 offset:47104
	s_waitcnt lgkmcnt(6)
	v_mfma_f32_32x32x16_bf16 v[32:47], v[80:83], v[64:67], v[32:47]
	ds_read_b64_tr_b16 v[72:73], v206 offset:40960
	ds_read_b64_tr_b16 v[74:75], v206 offset:43008
	ds_read_b64_tr_b16 v[80:81], v204 offset:45056
	ds_read_b64_tr_b16 v[82:83], v204 offset:47104
	s_waitcnt lgkmcnt(2)
	v_mfma_f32_32x32x16_bf16 v[0:15], v[72:75], v[64:67], v[0:15]
	v_add_f32_e32 v74, v205, v203
	v_add_f32_e32 v74, v92, v74
	v_add_f32_e32 v74, v93, v74
	v_add_f32_e32 v74, v94, v74
	v_add_f32_e32 v74, v95, v74
	v_add_f32_e32 v74, v146, v74
	v_add_f32_e32 v74, v147, v74
	v_mfma_f32_32x32x16_bf16 v[16:31], v[68:71], v[64:67], v[16:31]
	v_fma_f32 v68, v76, s3, -v197
	v_add_f32_e32 v74, v148, v74
	v_exp_f32_e32 v76, v68
	v_fma_f32 v68, v77, s3, -v197
	v_fma_f32 v64, v79, s3, -v197
	v_add_f32_e32 v74, v149, v74
	v_exp_f32_e32 v77, v68
	ds_read_b64_tr_b16 v[68:69], v206 offset:45056
	ds_read_b64_tr_b16 v[70:71], v206 offset:47104
	v_exp_f32_e32 v72, v78
	v_exp_f32_e32 v73, v64
	v_add_f32_e32 v74, v150, v74
	v_add_f32_e32 v74, v151, v74
	v_add_f32_e32 v74, v152, v74
	v_add_f32_e32 v74, v142, v74
	v_cvt_pk_bf16_f32 v64, v143, v144
	v_cvt_pk_bf16_f32 v65, v145, v153
	v_cvt_pk_bf16_f32 v66, v76, v77
	v_cvt_pk_bf16_f32 v67, v72, v73
	v_add_f32_e32 v74, v143, v74
	v_add_f32_e32 v74, v144, v74
	v_mfma_f32_32x32x16_bf16 v[48:63], v[84:87], v[64:67], v[48:63]
	v_add_f32_e32 v74, v145, v74
	v_add_f32_e32 v74, v153, v74
	v_add_f32_e32 v74, v76, v74
	v_add_f32_e32 v74, v77, v74
	v_add_f32_e32 v72, v72, v74
	v_add_f32_e32 v72, v73, v72
	v_add_f32_e32 v196, v196, v72
	v_mfma_f32_32x32x16_bf16 v[32:47], v[88:91], v[64:67], v[32:47]
	s_waitcnt lgkmcnt(2)
	v_mfma_f32_32x32x16_bf16 v[16:31], v[80:83], v[64:67], v[16:31]
	s_waitcnt lgkmcnt(0)
	v_mfma_f32_32x32x16_bf16 v[0:15], v[68:71], v[64:67], v[0:15]

.LBB0_186:
	v_cmp_le_u32_e32 vcc, s8, v119
	s_and_saveexec_b64 s[18:19], vcc
	s_cbranch_execz .LBB0_190
	ds_read_b128 v[220:223], v189
	ds_read_b128 v[68:71], v189 offset:4096
	ds_read_b128 v[224:227], v190
	ds_read_b128 v[198:201], v190 offset:4096
	ds_read_b128 v[228:231], v191
	ds_read_b128 v[202:205], v191 offset:4096
	ds_read_b128 v[232:235], v192
	ds_read_b128 v[206:209], v192 offset:4096
	s_waitcnt lgkmcnt(7)
	v_mfma_f32_32x32x16_bf16 v[80:95], v[220:223], v[96:99], 0
	s_waitcnt lgkmcnt(5)
	v_mfma_f32_32x32x16_bf16 v[80:95], v[224:227], v[100:103], v[80:95]
	s_waitcnt lgkmcnt(3)
	v_mfma_f32_32x32x16_bf16 v[80:95], v[228:231], v[104:107], v[80:95]
	s_waitcnt lgkmcnt(1)
	v_mfma_f32_32x32x16_bf16 v[80:95], v[232:235], v[108:111], v[80:95]
	s_waitcnt lgkmcnt(0)
	v_mfma_f32_32x32x16_bf16 v[64:79], v[68:71], v[96:99], 0
	v_mfma_f32_32x32x16_bf16 v[64:79], v[198:201], v[100:103], v[64:79]
	s_nop 9
	v_max_f32_e32 v198, v81, v81
	v_max_f32_e32 v199, v80, v80
	v_max_f32_e32 v198, v199, v198
	v_max3_f32 v198, v198, v82, v83
	v_max3_f32 v198, v198, v84, v85
	v_max3_f32 v198, v198, v86, v87
	v_max3_f32 v198, v198, v88, v89
	v_mfma_f32_32x32x16_bf16 v[64:79], v[202:205], v[104:107], v[64:79]
	v_max3_f32 v198, v198, v90, v91
	v_max3_f32 v198, v198, v92, v93
	v_max3_f32 v198, v198, v94, v95
	v_mfma_f32_32x32x16_bf16 v[64:79], v[206:209], v[108:111], v[64:79]
	s_nop 11
	v_max3_f32 v198, v198, v64, v65
	v_max3_f32 v198, v198, v66, v67
	v_max3_f32 v198, v198, v68, v69
	v_max3_f32 v198, v198, v70, v71
	v_max3_f32 v198, v198, v72, v73
	v_max3_f32 v198, v198, v74, v75
	v_max3_f32 v198, v198, v76, v77
	v_max3_f32 v198, v198, v78, v79
	v_mov_b32_e32 v199, v198
	s_nop 1
	v_permlane32_swap_b32_e32 v198, v199
	v_max_f32_e32 v198, v198, v199
	v_mul_f32_e32 v198, 0x3e38aa3b, v198
	v_add_f32_e32 v199, 0x41000000, v197
	v_cmp_gt_f32_e32 vcc, v198, v199
	s_cbranch_vccz .LBB0_189
	s_nop 0
	v_cndmask_b32_e32 v199, v197, v198, vcc
	v_sub_f32_e32 v197, v197, v199
	v_exp_f32_e32 v198, v197
	v_mov_b32_e32 v197, v199
	v_pk_mul_f32 v[62:63], v[62:63], v[198:199] op_sel_hi:[1,0]
	v_pk_mul_f32 v[60:61], v[60:61], v[198:199] op_sel_hi:[1,0]
	v_pk_mul_f32 v[58:59], v[58:59], v[198:199] op_sel_hi:[1,0]
	v_pk_mul_f32 v[56:57], v[56:57], v[198:199] op_sel_hi:[1,0]
	v_pk_mul_f32 v[54:55], v[54:55], v[198:199] op_sel_hi:[1,0]
	v_pk_mul_f32 v[52:53], v[52:53], v[198:199] op_sel_hi:[1,0]
	v_pk_mul_f32 v[50:51], v[50:51], v[198:199] op_sel_hi:[1,0]
	v_pk_mul_f32 v[48:49], v[48:49], v[198:199] op_sel_hi:[1,0]
	v_pk_mul_f32 v[46:47], v[46:47], v[198:199] op_sel_hi:[1,0]
	v_pk_mul_f32 v[44:45], v[44:45], v[198:199] op_sel_hi:[1,0]
	v_pk_mul_f32 v[42:43], v[42:43], v[198:199] op_sel_hi:[1,0]
	v_pk_mul_f32 v[40:41], v[40:41], v[198:199] op_sel_hi:[1,0]
	v_pk_mul_f32 v[38:39], v[38:39], v[198:199] op_sel_hi:[1,0]
	v_pk_mul_f32 v[36:37], v[36:37], v[198:199] op_sel_hi:[1,0]
	v_pk_mul_f32 v[34:35], v[34:35], v[198:199] op_sel_hi:[1,0]
	v_pk_mul_f32 v[32:33], v[32:33], v[198:199] op_sel_hi:[1,0]
	v_pk_mul_f32 v[30:31], v[30:31], v[198:199] op_sel_hi:[1,0]
	v_pk_mul_f32 v[28:29], v[28:29], v[198:199] op_sel_hi:[1,0]
	v_pk_mul_f32 v[26:27], v[26:27], v[198:199] op_sel_hi:[1,0]
	v_pk_mul_f32 v[24:25], v[24:25], v[198:199] op_sel_hi:[1,0]
	v_pk_mul_f32 v[22:23], v[22:23], v[198:199] op_sel_hi:[1,0]
	v_pk_mul_f32 v[20:21], v[20:21], v[198:199] op_sel_hi:[1,0]
	v_pk_mul_f32 v[18:19], v[18:19], v[198:199] op_sel_hi:[1,0]
	v_pk_mul_f32 v[16:17], v[16:17], v[198:199] op_sel_hi:[1,0]
	v_pk_mul_f32 v[14:15], v[14:15], v[198:199] op_sel_hi:[1,0]
	v_pk_mul_f32 v[12:13], v[12:13], v[198:199] op_sel_hi:[1,0]
	v_pk_mul_f32 v[10:11], v[10:11], v[198:199] op_sel_hi:[1,0]
	v_pk_mul_f32 v[8:9], v[8:9], v[198:199] op_sel_hi:[1,0]
	v_pk_mul_f32 v[6:7], v[6:7], v[198:199] op_sel_hi:[1,0]
	v_pk_mul_f32 v[4:5], v[4:5], v[198:199] op_sel_hi:[1,0]
	v_pk_mul_f32 v[2:3], v[2:3], v[198:199] op_sel_hi:[1,0]
	v_pk_mul_f32 v[0:1], v[0:1], v[198:199] op_sel_hi:[1,0]
	v_mul_f32_e32 v196, v196, v198
.LBB0_189:
	v_fma_f32 v80, v80, s3, -v197
	v_exp_f32_e32 v80, v80
	v_fma_f32 v81, v81, s3, -v197
	v_fma_f32 v82, v82, s3, -v197
	v_exp_f32_e32 v81, v81
	v_exp_f32_e32 v82, v82
	v_fma_f32 v83, v83, s3, -v197
	v_exp_f32_e32 v83, v83
	v_fma_f32 v84, v84, s3, -v197
	v_add_f32_e32 v198, 0, v80
	v_exp_f32_e32 v199, v84
	v_fma_f32 v85, v85, s3, -v197
	v_add_f32_e32 v84, v81, v198
	v_exp_f32_e32 v198, v85
	v_fma_f32 v85, v86, s3, -v197
	v_add_f32_e32 v84, v82, v84
	v_exp_f32_e32 v200, v85
	v_fma_f32 v85, v87, s3, -v197
	v_add_f32_e32 v84, v83, v84
	v_exp_f32_e32 v201, v85
	v_fma_f32 v85, v88, s3, -v197
	v_add_f32_e32 v84, v199, v84
	v_exp_f32_e32 v210, v85
	v_add_f32_e32 v84, v198, v84
	v_add_f32_e32 v84, v200, v84
	v_add_f32_e32 v84, v201, v84
	v_add_f32_e32 v88, v210, v84
	v_fma_f32 v84, v89, s3, -v197
	v_exp_f32_e32 v211, v84
	v_fma_f32 v84, v90, s3, -v197
	v_add_u32_e32 v213, v173, v168
	v_exp_f32_e32 v212, v84
	ds_read_b64_tr_b16 v[84:85], v213 offset:8192
	ds_read_b64_tr_b16 v[86:87], v213 offset:10240
	v_add_u32_e32 v214, v173, v169
	v_cvt_pk_bf16_f32 v80, v80, v81
	v_cvt_pk_bf16_f32 v81, v82, v83
	v_cvt_pk_bf16_f32 v82, v199, v198
	v_cvt_pk_bf16_f32 v83, v200, v201
	ds_read_b64_tr_b16 v[198:199], v214 offset:8192
	ds_read_b64_tr_b16 v[200:201], v214 offset:10240
	ds_read_b64_tr_b16 v[202:203], v213 offset:12288
	ds_read_b64_tr_b16 v[204:205], v213 offset:14336
	s_waitcnt lgkmcnt(4)
	v_mfma_f32_32x32x16_bf16 v[48:63], v[84:87], v[80:83], v[48:63]
	v_add_f32_e32 v84, v211, v88
	v_add_u32_e32 v216, v173, v170
	v_add_f32_e32 v215, v212, v84
	ds_read_b64_tr_b16 v[84:85], v216 offset:8192
	ds_read_b64_tr_b16 v[86:87], v216 offset:10240
	ds_read_b64_tr_b16 v[206:207], v214 offset:12288
	ds_read_b64_tr_b16 v[208:209], v214 offset:14336
	v_fma_f32 v88, v91, s3, -v197
	v_add_u32_e32 v218, v173, v171
	v_exp_f32_e32 v217, v88
	s_waitcnt lgkmcnt(6)
	v_mfma_f32_32x32x16_bf16 v[32:47], v[198:201], v[80:83], v[32:47]
	ds_read_b64_tr_b16 v[88:89], v218 offset:8192
	ds_read_b64_tr_b16 v[90:91], v218 offset:10240
	ds_read_b64_tr_b16 v[198:199], v216 offset:12288
	ds_read_b64_tr_b16 v[200:201], v216 offset:14336
	v_fma_f32 v94, v94, s3, -v197
	v_exp_f32_e32 v94, v94
	v_fma_f32 v64, v64, s3, -v197
	v_fma_f32 v78, v78, s3, -v197
	s_waitcnt lgkmcnt(6)
	v_mfma_f32_32x32x16_bf16 v[16:31], v[84:87], v[80:83], v[16:31]
	v_fma_f32 v84, v92, s3, -v197
	v_exp_f32_e32 v92, v84
	v_fma_f32 v84, v93, s3, -v197
	v_exp_f32_e32 v93, v84
	ds_read_b64_tr_b16 v[84:85], v218 offset:12288
	ds_read_b64_tr_b16 v[86:87], v218 offset:14336
	s_waitcnt lgkmcnt(4)
	v_mfma_f32_32x32x16_bf16 v[0:15], v[88:91], v[80:83], v[0:15]
	v_fma_f32 v80, v95, s3, -v197
	v_exp_f32_e32 v95, v80
	v_cvt_pk_bf16_f32 v80, v210, v211
	v_cvt_pk_bf16_f32 v81, v212, v217
	v_cvt_pk_bf16_f32 v82, v92, v93
	v_cvt_pk_bf16_f32 v83, v94, v95
	s_nop 1
	v_mfma_f32_32x32x16_bf16 v[48:63], v[202:205], v[80:83], v[48:63]
	v_exp_f32_e32 v202, v64
	v_fma_f32 v64, v65, s3, -v197
	v_exp_f32_e32 v203, v64
	v_fma_f32 v64, v66, s3, -v197
	v_exp_f32_e32 v204, v64
	v_fma_f32 v64, v67, s3, -v197
	v_exp_f32_e32 v205, v64
	v_fma_f32 v64, v68, s3, -v197
	v_mfma_f32_32x32x16_bf16 v[32:47], v[206:209], v[80:83], v[32:47]
	v_exp_f32_e32 v206, v64
	v_fma_f32 v64, v69, s3, -v197
	v_exp_f32_e32 v207, v64
	v_fma_f32 v64, v70, s3, -v197
	v_exp_f32_e32 v208, v64
	v_fma_f32 v64, v71, s3, -v197
	ds_read_b64_tr_b16 v[68:69], v213 offset:16384
	ds_read_b64_tr_b16 v[70:71], v213 offset:18432
	s_waitcnt lgkmcnt(4)
	v_mfma_f32_32x32x16_bf16 v[16:31], v[198:201], v[80:83], v[16:31]
	v_exp_f32_e32 v198, v64
	v_fma_f32 v64, v72, s3, -v197
	v_exp_f32_e32 v199, v64
	v_cvt_pk_bf16_f32 v64, v202, v203
	v_cvt_pk_bf16_f32 v65, v204, v205
	v_cvt_pk_bf16_f32 v66, v206, v207
	v_cvt_pk_bf16_f32 v67, v208, v198
	s_waitcnt lgkmcnt(2)
	v_mfma_f32_32x32x16_bf16 v[0:15], v[84:87], v[80:83], v[0:15]
	ds_read_b64_tr_b16 v[80:81], v214 offset:16384
	ds_read_b64_tr_b16 v[82:83], v214 offset:18432
	ds_read_b64_tr_b16 v[84:85], v213 offset:20480
	ds_read_b64_tr_b16 v[86:87], v213 offset:22528
	v_fma_f32 v72, v74, s3, -v197
	v_exp_f32_e32 v201, v72
	v_fma_f32 v72, v75, s3, -v197
	v_exp_f32_e32 v209, v72
	s_waitcnt lgkmcnt(4)
	v_mfma_f32_32x32x16_bf16 v[48:63], v[68:71], v[64:67], v[48:63]
	v_fma_f32 v68, v73, s3, -v197
	v_exp_f32_e32 v200, v68
	ds_read_b64_tr_b16 v[68:69], v216 offset:16384
	ds_read_b64_tr_b16 v[70:71], v216 offset:18432
	ds_read_b64_tr_b16 v[88:89], v214 offset:20480
	ds_read_b64_tr_b16 v[90:91], v214 offset:22528
	s_waitcnt lgkmcnt(6)
	v_mfma_f32_32x32x16_bf16 v[32:47], v[80:83], v[64:67], v[32:47]
	ds_read_b64_tr_b16 v[72:73], v218 offset:16384
	ds_read_b64_tr_b16 v[74:75], v218 offset:18432
	ds_read_b64_tr_b16 v[80:81], v216 offset:20480
	ds_read_b64_tr_b16 v[82:83], v216 offset:22528
	s_waitcnt lgkmcnt(2)
	v_mfma_f32_32x32x16_bf16 v[0:15], v[72:75], v[64:67], v[0:15]
	v_add_f32_e32 v74, v217, v215
	v_add_f32_e32 v74, v92, v74
	v_add_f32_e32 v74, v93, v74
	v_add_f32_e32 v74, v94, v74
	v_add_f32_e32 v74, v95, v74
	v_add_f32_e32 v74, v202, v74
	v_add_f32_e32 v74, v203, v74
	v_mfma_f32_32x32x16_bf16 v[16:31], v[68:71], v[64:67], v[16:31]
	v_fma_f32 v68, v76, s3, -v197
	v_add_f32_e32 v74, v204, v74
	v_exp_f32_e32 v76, v68
	v_fma_f32 v68, v77, s3, -v197
	v_fma_f32 v64, v79, s3, -v197
	v_add_f32_e32 v74, v205, v74
	v_exp_f32_e32 v77, v68
	ds_read_b64_tr_b16 v[68:69], v218 offset:20480
	ds_read_b64_tr_b16 v[70:71], v218 offset:22528
	v_exp_f32_e32 v72, v78
	v_exp_f32_e32 v73, v64
	v_add_f32_e32 v74, v206, v74
	v_add_f32_e32 v74, v207, v74
	v_add_f32_e32 v74, v208, v74
	v_add_f32_e32 v74, v198, v74
	v_cvt_pk_bf16_f32 v64, v199, v200
	v_cvt_pk_bf16_f32 v65, v201, v209
	v_cvt_pk_bf16_f32 v66, v76, v77
	v_cvt_pk_bf16_f32 v67, v72, v73
	v_add_f32_e32 v74, v199, v74
	v_add_f32_e32 v74, v200, v74
	v_mfma_f32_32x32x16_bf16 v[48:63], v[84:87], v[64:67], v[48:63]
	v_add_f32_e32 v74, v201, v74
	v_add_f32_e32 v74, v209, v74
	v_add_f32_e32 v74, v76, v74
	v_add_f32_e32 v74, v77, v74
	v_add_f32_e32 v72, v72, v74
	v_add_f32_e32 v72, v73, v72
	v_add_f32_e32 v196, v196, v72
	v_mfma_f32_32x32x16_bf16 v[32:47], v[88:91], v[64:67], v[32:47]
	s_waitcnt lgkmcnt(2)
	v_mfma_f32_32x32x16_bf16 v[16:31], v[80:83], v[64:67], v[16:31]
	s_waitcnt lgkmcnt(0)
	v_mfma_f32_32x32x16_bf16 v[0:15], v[68:71], v[64:67], v[0:15]

.LBB0_192:
	v_cmp_lt_u32_e32 vcc, s8, v119
	s_and_saveexec_b64 s[18:19], vcc
	s_cbranch_execz .LBB0_183
	ds_read_b128 v[220:223], v189 offset:24576
	ds_read_b128 v[68:71], v189 offset:28672
	ds_read_b128 v[224:227], v190 offset:24576
	ds_read_b128 v[142:145], v190 offset:28672
	ds_read_b128 v[228:231], v191 offset:24576
	ds_read_b128 v[146:149], v191 offset:28672
	ds_read_b128 v[232:235], v192 offset:24576
	ds_read_b128 v[150:153], v192 offset:28672
	s_waitcnt lgkmcnt(7)
	v_mfma_f32_32x32x16_bf16 v[80:95], v[220:223], v[96:99], 0
	s_waitcnt lgkmcnt(5)
	v_mfma_f32_32x32x16_bf16 v[80:95], v[224:227], v[100:103], v[80:95]
	s_waitcnt lgkmcnt(3)
	v_mfma_f32_32x32x16_bf16 v[80:95], v[228:231], v[104:107], v[80:95]
	s_waitcnt lgkmcnt(1)
	v_mfma_f32_32x32x16_bf16 v[80:95], v[232:235], v[108:111], v[80:95]
	s_waitcnt lgkmcnt(0)
	v_mfma_f32_32x32x16_bf16 v[64:79], v[68:71], v[96:99], 0
	v_mfma_f32_32x32x16_bf16 v[64:79], v[142:145], v[100:103], v[64:79]
	s_nop 9
	v_max_f32_e32 v142, v81, v81
	v_max_f32_e32 v143, v80, v80
	v_max_f32_e32 v142, v143, v142
	v_max3_f32 v142, v142, v82, v83
	v_max3_f32 v142, v142, v84, v85
	v_max3_f32 v142, v142, v86, v87
	v_max3_f32 v142, v142, v88, v89
	v_mfma_f32_32x32x16_bf16 v[64:79], v[146:149], v[104:107], v[64:79]
	v_max3_f32 v142, v142, v90, v91
	v_max3_f32 v142, v142, v92, v93
	v_max3_f32 v142, v142, v94, v95
	v_mfma_f32_32x32x16_bf16 v[64:79], v[150:153], v[108:111], v[64:79]
	s_nop 11
	v_max3_f32 v142, v142, v64, v65
	v_max3_f32 v142, v142, v66, v67
	v_max3_f32 v142, v142, v68, v69
	v_max3_f32 v142, v142, v70, v71
	v_max3_f32 v142, v142, v72, v73
	v_max3_f32 v142, v142, v74, v75
	v_max3_f32 v142, v142, v76, v77
	v_max3_f32 v142, v142, v78, v79
	v_mov_b32_e32 v143, v142
	s_nop 1
	v_permlane32_swap_b32_e32 v142, v143
	v_max_f32_e32 v142, v142, v143
	v_mul_f32_e32 v142, 0x3e38aa3b, v142
	v_add_f32_e32 v143, 0x41000000, v197
	v_cmp_gt_f32_e32 vcc, v142, v143
	s_cbranch_vccz .LBB0_182
	s_nop 0
	v_cndmask_b32_e32 v143, v197, v142, vcc
	v_sub_f32_e32 v142, v197, v143
	v_exp_f32_e32 v142, v142
	v_mov_b32_e32 v197, v143
	v_pk_mul_f32 v[62:63], v[62:63], v[142:143] op_sel_hi:[1,0]
	v_pk_mul_f32 v[60:61], v[60:61], v[142:143] op_sel_hi:[1,0]
	v_pk_mul_f32 v[58:59], v[58:59], v[142:143] op_sel_hi:[1,0]
	v_pk_mul_f32 v[56:57], v[56:57], v[142:143] op_sel_hi:[1,0]
	v_pk_mul_f32 v[54:55], v[54:55], v[142:143] op_sel_hi:[1,0]
	v_pk_mul_f32 v[52:53], v[52:53], v[142:143] op_sel_hi:[1,0]
	v_pk_mul_f32 v[50:51], v[50:51], v[142:143] op_sel_hi:[1,0]
	v_pk_mul_f32 v[48:49], v[48:49], v[142:143] op_sel_hi:[1,0]
	v_pk_mul_f32 v[46:47], v[46:47], v[142:143] op_sel_hi:[1,0]
	v_pk_mul_f32 v[44:45], v[44:45], v[142:143] op_sel_hi:[1,0]
	v_pk_mul_f32 v[42:43], v[42:43], v[142:143] op_sel_hi:[1,0]
	v_pk_mul_f32 v[40:41], v[40:41], v[142:143] op_sel_hi:[1,0]
	v_pk_mul_f32 v[38:39], v[38:39], v[142:143] op_sel_hi:[1,0]
	v_pk_mul_f32 v[36:37], v[36:37], v[142:143] op_sel_hi:[1,0]
	v_pk_mul_f32 v[34:35], v[34:35], v[142:143] op_sel_hi:[1,0]
	v_pk_mul_f32 v[32:33], v[32:33], v[142:143] op_sel_hi:[1,0]
	v_pk_mul_f32 v[30:31], v[30:31], v[142:143] op_sel_hi:[1,0]
	v_pk_mul_f32 v[28:29], v[28:29], v[142:143] op_sel_hi:[1,0]
	v_pk_mul_f32 v[26:27], v[26:27], v[142:143] op_sel_hi:[1,0]
	v_pk_mul_f32 v[24:25], v[24:25], v[142:143] op_sel_hi:[1,0]
	v_pk_mul_f32 v[22:23], v[22:23], v[142:143] op_sel_hi:[1,0]
	v_pk_mul_f32 v[20:21], v[20:21], v[142:143] op_sel_hi:[1,0]
	v_pk_mul_f32 v[18:19], v[18:19], v[142:143] op_sel_hi:[1,0]
	v_pk_mul_f32 v[16:17], v[16:17], v[142:143] op_sel_hi:[1,0]
	v_pk_mul_f32 v[14:15], v[14:15], v[142:143] op_sel_hi:[1,0]
	v_pk_mul_f32 v[12:13], v[12:13], v[142:143] op_sel_hi:[1,0]
	v_pk_mul_f32 v[10:11], v[10:11], v[142:143] op_sel_hi:[1,0]
	v_pk_mul_f32 v[8:9], v[8:9], v[142:143] op_sel_hi:[1,0]
	v_pk_mul_f32 v[6:7], v[6:7], v[142:143] op_sel_hi:[1,0]
	v_pk_mul_f32 v[4:5], v[4:5], v[142:143] op_sel_hi:[1,0]
	v_pk_mul_f32 v[2:3], v[2:3], v[142:143] op_sel_hi:[1,0]
	v_pk_mul_f32 v[0:1], v[0:1], v[142:143] op_sel_hi:[1,0]
	v_mul_f32_e32 v196, v196, v142
	s_branch .LBB0_182

.LBB0_196:
	v_fma_f32 v80, v80, s3, -v145
	v_exp_f32_e32 v80, v80
	v_fma_f32 v81, v81, s3, -v145
	v_fma_f32 v82, v82, s3, -v145
	v_exp_f32_e32 v81, v81
	v_exp_f32_e32 v82, v82
	v_fma_f32 v83, v83, s3, -v145
	v_exp_f32_e32 v83, v83
	v_fma_f32 v84, v84, s3, -v145
	v_add_f32_e32 v132, 0, v80
	v_exp_f32_e32 v133, v84
	v_fma_f32 v85, v85, s3, -v145
	v_add_f32_e32 v84, v81, v132
	v_exp_f32_e32 v132, v85
	v_fma_f32 v85, v86, s3, -v145
	v_add_f32_e32 v84, v82, v84
	v_exp_f32_e32 v134, v85
	v_fma_f32 v85, v87, s3, -v145
	v_add_f32_e32 v84, v83, v84
	v_exp_f32_e32 v135, v85
	v_fma_f32 v85, v88, s3, -v145
	v_add_f32_e32 v84, v133, v84
	v_exp_f32_e32 v146, v85
	v_add_f32_e32 v84, v132, v84
	v_add_f32_e32 v84, v134, v84
	v_add_f32_e32 v84, v135, v84
	v_add_f32_e32 v88, v146, v84
	v_fma_f32 v84, v89, s3, -v145
	v_exp_f32_e32 v147, v84
	v_fma_f32 v84, v90, s3, -v145
	v_add_u32_e32 v149, v173, v168
	v_exp_f32_e32 v148, v84
	ds_read_b64_tr_b16 v[84:85], v149 offset:32768
	ds_read_b64_tr_b16 v[86:87], v149 offset:34816
	v_add_u32_e32 v150, v173, v169
	v_cvt_pk_bf16_f32 v80, v80, v81
	v_cvt_pk_bf16_f32 v81, v82, v83
	v_cvt_pk_bf16_f32 v82, v133, v132
	v_cvt_pk_bf16_f32 v83, v134, v135
	ds_read_b64_tr_b16 v[132:133], v150 offset:32768
	ds_read_b64_tr_b16 v[134:135], v150 offset:34816
	ds_read_b64_tr_b16 v[136:137], v149 offset:36864
	ds_read_b64_tr_b16 v[138:139], v149 offset:38912
	s_waitcnt lgkmcnt(4)
	v_mfma_f32_32x32x16_bf16 v[48:63], v[84:87], v[80:83], v[48:63]
	v_add_f32_e32 v84, v147, v88
	v_add_u32_e32 v152, v173, v170
	v_add_f32_e32 v151, v148, v84
	ds_read_b64_tr_b16 v[84:85], v152 offset:32768
	ds_read_b64_tr_b16 v[86:87], v152 offset:34816
	ds_read_b64_tr_b16 v[140:141], v150 offset:36864
	ds_read_b64_tr_b16 v[142:143], v150 offset:38912
	v_fma_f32 v88, v91, s3, -v145
	v_add_u32_e32 v194, v173, v171
	v_exp_f32_e32 v153, v88
	s_waitcnt lgkmcnt(6)
	v_mfma_f32_32x32x16_bf16 v[32:47], v[132:135], v[80:83], v[32:47]
	ds_read_b64_tr_b16 v[88:89], v194 offset:32768
	ds_read_b64_tr_b16 v[90:91], v194 offset:34816
	ds_read_b64_tr_b16 v[132:133], v152 offset:36864
	ds_read_b64_tr_b16 v[134:135], v152 offset:38912
	v_fma_f32 v94, v94, s3, -v145
	v_exp_f32_e32 v94, v94
	v_fma_f32 v64, v64, s3, -v145
	v_fma_f32 v78, v78, s3, -v145
	s_waitcnt lgkmcnt(6)
	v_mfma_f32_32x32x16_bf16 v[16:31], v[84:87], v[80:83], v[16:31]
	v_fma_f32 v84, v92, s3, -v145
	v_exp_f32_e32 v92, v84
	v_fma_f32 v84, v93, s3, -v145
	v_exp_f32_e32 v93, v84
	ds_read_b64_tr_b16 v[84:85], v194 offset:36864
	ds_read_b64_tr_b16 v[86:87], v194 offset:38912
	s_waitcnt lgkmcnt(4)
	v_mfma_f32_32x32x16_bf16 v[0:15], v[88:91], v[80:83], v[0:15]
	v_fma_f32 v80, v95, s3, -v145
	v_exp_f32_e32 v95, v80
	v_cvt_pk_bf16_f32 v80, v146, v147
	v_cvt_pk_bf16_f32 v81, v148, v153
	v_cvt_pk_bf16_f32 v82, v92, v93
	v_cvt_pk_bf16_f32 v83, v94, v95
	s_nop 1
	v_mfma_f32_32x32x16_bf16 v[48:63], v[136:139], v[80:83], v[48:63]
	v_exp_f32_e32 v136, v64
	v_fma_f32 v64, v65, s3, -v145
	v_exp_f32_e32 v137, v64
	v_fma_f32 v64, v66, s3, -v145
	v_exp_f32_e32 v138, v64
	v_fma_f32 v64, v67, s3, -v145
	v_exp_f32_e32 v139, v64
	v_fma_f32 v64, v68, s3, -v145
	v_mfma_f32_32x32x16_bf16 v[32:47], v[140:143], v[80:83], v[32:47]
	v_exp_f32_e32 v140, v64
	v_fma_f32 v64, v69, s3, -v145
	v_exp_f32_e32 v141, v64
	v_fma_f32 v64, v70, s3, -v145
	v_exp_f32_e32 v142, v64
	v_fma_f32 v64, v71, s3, -v145
	ds_read_b64_tr_b16 v[68:69], v149 offset:40960
	ds_read_b64_tr_b16 v[70:71], v149 offset:43008
	s_waitcnt lgkmcnt(4)
	v_mfma_f32_32x32x16_bf16 v[16:31], v[132:135], v[80:83], v[16:31]
	v_exp_f32_e32 v132, v64
	v_fma_f32 v64, v72, s3, -v145
	v_exp_f32_e32 v133, v64
	v_cvt_pk_bf16_f32 v64, v136, v137
	v_cvt_pk_bf16_f32 v65, v138, v139
	v_cvt_pk_bf16_f32 v66, v140, v141
	v_cvt_pk_bf16_f32 v67, v142, v132
	s_waitcnt lgkmcnt(2)
	v_mfma_f32_32x32x16_bf16 v[0:15], v[84:87], v[80:83], v[0:15]
	ds_read_b64_tr_b16 v[80:81], v150 offset:40960
	ds_read_b64_tr_b16 v[82:83], v150 offset:43008
	ds_read_b64_tr_b16 v[84:85], v149 offset:45056
	ds_read_b64_tr_b16 v[86:87], v149 offset:47104
	v_fma_f32 v72, v74, s3, -v145
	v_exp_f32_e32 v135, v72
	v_fma_f32 v72, v75, s3, -v145
	v_exp_f32_e32 v143, v72
	s_waitcnt lgkmcnt(4)
	v_mfma_f32_32x32x16_bf16 v[48:63], v[68:71], v[64:67], v[48:63]
	v_fma_f32 v68, v73, s3, -v145
	v_exp_f32_e32 v134, v68
	ds_read_b64_tr_b16 v[68:69], v152 offset:40960
	ds_read_b64_tr_b16 v[70:71], v152 offset:43008
	ds_read_b64_tr_b16 v[88:89], v150 offset:45056
	ds_read_b64_tr_b16 v[90:91], v150 offset:47104
	s_waitcnt lgkmcnt(6)
	v_mfma_f32_32x32x16_bf16 v[32:47], v[80:83], v[64:67], v[32:47]
	ds_read_b64_tr_b16 v[72:73], v194 offset:40960
	ds_read_b64_tr_b16 v[74:75], v194 offset:43008
	ds_read_b64_tr_b16 v[80:81], v152 offset:45056
	ds_read_b64_tr_b16 v[82:83], v152 offset:47104
	s_waitcnt lgkmcnt(2)
	v_mfma_f32_32x32x16_bf16 v[0:15], v[72:75], v[64:67], v[0:15]
	v_add_f32_e32 v74, v153, v151
	v_add_f32_e32 v74, v92, v74
	v_add_f32_e32 v74, v93, v74
	v_add_f32_e32 v74, v94, v74
	v_add_f32_e32 v74, v95, v74
	v_add_f32_e32 v74, v136, v74
	v_add_f32_e32 v74, v137, v74
	v_mfma_f32_32x32x16_bf16 v[16:31], v[68:71], v[64:67], v[16:31]
	v_fma_f32 v68, v76, s3, -v145
	v_add_f32_e32 v74, v138, v74
	v_exp_f32_e32 v76, v68
	v_fma_f32 v68, v77, s3, -v145
	v_fma_f32 v64, v79, s3, -v145
	v_add_f32_e32 v74, v139, v74
	v_exp_f32_e32 v77, v68
	ds_read_b64_tr_b16 v[68:69], v194 offset:45056
	ds_read_b64_tr_b16 v[70:71], v194 offset:47104
	v_exp_f32_e32 v72, v78
	v_exp_f32_e32 v73, v64
	v_add_f32_e32 v74, v140, v74
	v_add_f32_e32 v74, v141, v74
	v_add_f32_e32 v74, v142, v74
	v_add_f32_e32 v74, v132, v74
	v_cvt_pk_bf16_f32 v64, v133, v134
	v_cvt_pk_bf16_f32 v65, v135, v143
	v_cvt_pk_bf16_f32 v66, v76, v77
	v_cvt_pk_bf16_f32 v67, v72, v73
	v_add_f32_e32 v74, v133, v74
	v_add_f32_e32 v74, v134, v74
	v_mfma_f32_32x32x16_bf16 v[48:63], v[84:87], v[64:67], v[48:63]
	v_add_f32_e32 v74, v135, v74
	v_add_f32_e32 v74, v143, v74
	v_add_f32_e32 v74, v76, v74
	v_add_f32_e32 v74, v77, v74
	v_add_f32_e32 v72, v72, v74
	v_add_f32_e32 v72, v73, v72
	v_add_f32_e32 v144, v144, v72
	v_mfma_f32_32x32x16_bf16 v[32:47], v[88:91], v[64:67], v[32:47]
	s_waitcnt lgkmcnt(2)
	v_mfma_f32_32x32x16_bf16 v[16:31], v[80:83], v[64:67], v[16:31]
	s_waitcnt lgkmcnt(0)
	v_mfma_f32_32x32x16_bf16 v[0:15], v[68:71], v[64:67], v[0:15]

.LBB0_200:
	v_cmp_le_u32_e32 vcc, s8, v119
	s_and_saveexec_b64 s[14:15], vcc
	s_cbranch_execz .LBB0_204
	ds_read_b128 v[220:223], v189
	ds_read_b128 v[68:71], v189 offset:4096
	ds_read_b128 v[224:227], v190
	ds_read_b128 v[146:149], v190 offset:4096
	ds_read_b128 v[228:231], v191
	ds_read_b128 v[150:153], v191 offset:4096
	ds_read_b128 v[232:235], v192
	ds_read_b128 v[194:197], v192 offset:4096
	s_waitcnt lgkmcnt(7)
	v_mfma_f32_32x32x16_bf16 v[80:95], v[220:223], v[96:99], 0
	s_waitcnt lgkmcnt(5)
	v_mfma_f32_32x32x16_bf16 v[80:95], v[224:227], v[100:103], v[80:95]
	s_waitcnt lgkmcnt(3)
	v_mfma_f32_32x32x16_bf16 v[80:95], v[228:231], v[104:107], v[80:95]
	s_waitcnt lgkmcnt(1)
	v_mfma_f32_32x32x16_bf16 v[80:95], v[232:235], v[108:111], v[80:95]
	s_waitcnt lgkmcnt(0)
	v_mfma_f32_32x32x16_bf16 v[64:79], v[68:71], v[96:99], 0
	v_mfma_f32_32x32x16_bf16 v[64:79], v[146:149], v[100:103], v[64:79]
	s_nop 9
	v_max_f32_e32 v146, v81, v81
	v_max_f32_e32 v147, v80, v80
	v_max_f32_e32 v146, v147, v146
	v_max3_f32 v146, v146, v82, v83
	v_max3_f32 v146, v146, v84, v85
	v_max3_f32 v146, v146, v86, v87
	v_max3_f32 v146, v146, v88, v89
	v_mfma_f32_32x32x16_bf16 v[64:79], v[150:153], v[104:107], v[64:79]
	v_max3_f32 v146, v146, v90, v91
	v_max3_f32 v146, v146, v92, v93
	v_max3_f32 v146, v146, v94, v95
	v_mfma_f32_32x32x16_bf16 v[64:79], v[194:197], v[108:111], v[64:79]
	s_nop 11
	v_max3_f32 v146, v146, v64, v65
	v_max3_f32 v146, v146, v66, v67
	v_max3_f32 v146, v146, v68, v69
	v_max3_f32 v146, v146, v70, v71
	v_max3_f32 v146, v146, v72, v73
	v_max3_f32 v146, v146, v74, v75
	v_max3_f32 v146, v146, v76, v77
	v_max3_f32 v146, v146, v78, v79
	v_mov_b32_e32 v147, v146
	s_nop 1
	v_permlane32_swap_b32_e32 v146, v147
	v_max_f32_e32 v146, v146, v147
	v_mul_f32_e32 v146, 0x3e38aa3b, v146
	v_add_f32_e32 v147, 0x41000000, v145
	v_cmp_gt_f32_e32 vcc, v146, v147
	s_cbranch_vccz .LBB0_203
	s_nop 0
	v_cndmask_b32_e32 v147, v145, v146, vcc
	v_sub_f32_e32 v145, v145, v147
	v_exp_f32_e32 v146, v145
	v_mov_b32_e32 v145, v147
	v_pk_mul_f32 v[62:63], v[62:63], v[146:147] op_sel_hi:[1,0]
	v_pk_mul_f32 v[60:61], v[60:61], v[146:147] op_sel_hi:[1,0]
	v_pk_mul_f32 v[58:59], v[58:59], v[146:147] op_sel_hi:[1,0]
	v_pk_mul_f32 v[56:57], v[56:57], v[146:147] op_sel_hi:[1,0]
	v_pk_mul_f32 v[54:55], v[54:55], v[146:147] op_sel_hi:[1,0]
	v_pk_mul_f32 v[52:53], v[52:53], v[146:147] op_sel_hi:[1,0]
	v_pk_mul_f32 v[50:51], v[50:51], v[146:147] op_sel_hi:[1,0]
	v_pk_mul_f32 v[48:49], v[48:49], v[146:147] op_sel_hi:[1,0]
	v_pk_mul_f32 v[46:47], v[46:47], v[146:147] op_sel_hi:[1,0]
	v_pk_mul_f32 v[44:45], v[44:45], v[146:147] op_sel_hi:[1,0]
	v_pk_mul_f32 v[42:43], v[42:43], v[146:147] op_sel_hi:[1,0]
	v_pk_mul_f32 v[40:41], v[40:41], v[146:147] op_sel_hi:[1,0]
	v_pk_mul_f32 v[38:39], v[38:39], v[146:147] op_sel_hi:[1,0]
	v_pk_mul_f32 v[36:37], v[36:37], v[146:147] op_sel_hi:[1,0]
	v_pk_mul_f32 v[34:35], v[34:35], v[146:147] op_sel_hi:[1,0]
	v_pk_mul_f32 v[32:33], v[32:33], v[146:147] op_sel_hi:[1,0]
	v_pk_mul_f32 v[30:31], v[30:31], v[146:147] op_sel_hi:[1,0]
	v_pk_mul_f32 v[28:29], v[28:29], v[146:147] op_sel_hi:[1,0]
	v_pk_mul_f32 v[26:27], v[26:27], v[146:147] op_sel_hi:[1,0]
	v_pk_mul_f32 v[24:25], v[24:25], v[146:147] op_sel_hi:[1,0]
	v_pk_mul_f32 v[22:23], v[22:23], v[146:147] op_sel_hi:[1,0]
	v_pk_mul_f32 v[20:21], v[20:21], v[146:147] op_sel_hi:[1,0]
	v_pk_mul_f32 v[18:19], v[18:19], v[146:147] op_sel_hi:[1,0]
	v_pk_mul_f32 v[16:17], v[16:17], v[146:147] op_sel_hi:[1,0]
	v_pk_mul_f32 v[14:15], v[14:15], v[146:147] op_sel_hi:[1,0]
	v_pk_mul_f32 v[12:13], v[12:13], v[146:147] op_sel_hi:[1,0]
	v_pk_mul_f32 v[10:11], v[10:11], v[146:147] op_sel_hi:[1,0]
	v_pk_mul_f32 v[8:9], v[8:9], v[146:147] op_sel_hi:[1,0]
	v_pk_mul_f32 v[6:7], v[6:7], v[146:147] op_sel_hi:[1,0]
	v_pk_mul_f32 v[4:5], v[4:5], v[146:147] op_sel_hi:[1,0]
	v_pk_mul_f32 v[2:3], v[2:3], v[146:147] op_sel_hi:[1,0]
	v_pk_mul_f32 v[0:1], v[0:1], v[146:147] op_sel_hi:[1,0]
	v_mul_f32_e32 v144, v144, v146
.LBB0_203:
	v_fma_f32 v80, v80, s3, -v145
	v_exp_f32_e32 v80, v80
	v_fma_f32 v81, v81, s3, -v145
	v_fma_f32 v82, v82, s3, -v145
	v_exp_f32_e32 v81, v81
	v_exp_f32_e32 v82, v82
	v_fma_f32 v83, v83, s3, -v145
	v_exp_f32_e32 v83, v83
	v_fma_f32 v84, v84, s3, -v145
	v_add_f32_e32 v146, 0, v80
	v_exp_f32_e32 v147, v84
	v_fma_f32 v85, v85, s3, -v145
	v_add_f32_e32 v84, v81, v146
	v_exp_f32_e32 v146, v85
	v_fma_f32 v85, v86, s3, -v145
	v_add_f32_e32 v84, v82, v84
	v_exp_f32_e32 v148, v85
	v_fma_f32 v85, v87, s3, -v145
	v_add_f32_e32 v84, v83, v84
	v_exp_f32_e32 v149, v85
	v_fma_f32 v85, v88, s3, -v145
	v_add_f32_e32 v84, v147, v84
	v_exp_f32_e32 v198, v85
	v_add_f32_e32 v84, v146, v84
	v_add_f32_e32 v84, v148, v84
	v_add_f32_e32 v84, v149, v84
	v_add_f32_e32 v88, v198, v84
	v_fma_f32 v84, v89, s3, -v145
	v_exp_f32_e32 v199, v84
	v_fma_f32 v84, v90, s3, -v145
	v_add_u32_e32 v201, v173, v168
	v_exp_f32_e32 v200, v84
	ds_read_b64_tr_b16 v[84:85], v201 offset:8192
	ds_read_b64_tr_b16 v[86:87], v201 offset:10240
	v_add_u32_e32 v202, v173, v169
	v_cvt_pk_bf16_f32 v80, v80, v81
	v_cvt_pk_bf16_f32 v81, v82, v83
	v_cvt_pk_bf16_f32 v82, v147, v146
	v_cvt_pk_bf16_f32 v83, v148, v149
	ds_read_b64_tr_b16 v[146:147], v202 offset:8192
	ds_read_b64_tr_b16 v[148:149], v202 offset:10240
	ds_read_b64_tr_b16 v[150:151], v201 offset:12288
	ds_read_b64_tr_b16 v[152:153], v201 offset:14336
	s_waitcnt lgkmcnt(4)
	v_mfma_f32_32x32x16_bf16 v[48:63], v[84:87], v[80:83], v[48:63]
	v_add_f32_e32 v84, v199, v88
	v_add_u32_e32 v204, v173, v170
	v_add_f32_e32 v203, v200, v84
	ds_read_b64_tr_b16 v[84:85], v204 offset:8192
	ds_read_b64_tr_b16 v[86:87], v204 offset:10240
	ds_read_b64_tr_b16 v[194:195], v202 offset:12288
	ds_read_b64_tr_b16 v[196:197], v202 offset:14336
	v_fma_f32 v88, v91, s3, -v145
	v_add_u32_e32 v206, v173, v171
	v_exp_f32_e32 v205, v88
	s_waitcnt lgkmcnt(6)
	v_mfma_f32_32x32x16_bf16 v[32:47], v[146:149], v[80:83], v[32:47]
	ds_read_b64_tr_b16 v[88:89], v206 offset:8192
	ds_read_b64_tr_b16 v[90:91], v206 offset:10240
	ds_read_b64_tr_b16 v[146:147], v204 offset:12288
	ds_read_b64_tr_b16 v[148:149], v204 offset:14336
	v_fma_f32 v94, v94, s3, -v145
	v_exp_f32_e32 v94, v94
	v_fma_f32 v64, v64, s3, -v145
	v_fma_f32 v78, v78, s3, -v145
	s_waitcnt lgkmcnt(6)
	v_mfma_f32_32x32x16_bf16 v[16:31], v[84:87], v[80:83], v[16:31]
	v_fma_f32 v84, v92, s3, -v145
	v_exp_f32_e32 v92, v84
	v_fma_f32 v84, v93, s3, -v145
	v_exp_f32_e32 v93, v84
	ds_read_b64_tr_b16 v[84:85], v206 offset:12288
	ds_read_b64_tr_b16 v[86:87], v206 offset:14336
	s_waitcnt lgkmcnt(4)
	v_mfma_f32_32x32x16_bf16 v[0:15], v[88:91], v[80:83], v[0:15]
	v_fma_f32 v80, v95, s3, -v145
	v_exp_f32_e32 v95, v80
	v_cvt_pk_bf16_f32 v80, v198, v199
	v_cvt_pk_bf16_f32 v81, v200, v205
	v_cvt_pk_bf16_f32 v82, v92, v93
	v_cvt_pk_bf16_f32 v83, v94, v95
	s_nop 1
	v_mfma_f32_32x32x16_bf16 v[48:63], v[150:153], v[80:83], v[48:63]
	v_exp_f32_e32 v150, v64
	v_fma_f32 v64, v65, s3, -v145
	v_exp_f32_e32 v151, v64
	v_fma_f32 v64, v66, s3, -v145
	v_exp_f32_e32 v152, v64
	v_fma_f32 v64, v67, s3, -v145
	v_exp_f32_e32 v153, v64
	v_fma_f32 v64, v68, s3, -v145
	v_mfma_f32_32x32x16_bf16 v[32:47], v[194:197], v[80:83], v[32:47]
	v_exp_f32_e32 v194, v64
	v_fma_f32 v64, v69, s3, -v145
	v_exp_f32_e32 v195, v64
	v_fma_f32 v64, v70, s3, -v145
	v_exp_f32_e32 v196, v64
	v_fma_f32 v64, v71, s3, -v145
	ds_read_b64_tr_b16 v[68:69], v201 offset:16384
	ds_read_b64_tr_b16 v[70:71], v201 offset:18432
	s_waitcnt lgkmcnt(4)
	v_mfma_f32_32x32x16_bf16 v[16:31], v[146:149], v[80:83], v[16:31]
	v_exp_f32_e32 v146, v64
	v_fma_f32 v64, v72, s3, -v145
	v_exp_f32_e32 v147, v64
	v_cvt_pk_bf16_f32 v64, v150, v151
	v_cvt_pk_bf16_f32 v65, v152, v153
	v_cvt_pk_bf16_f32 v66, v194, v195
	v_cvt_pk_bf16_f32 v67, v196, v146
	s_waitcnt lgkmcnt(2)
	v_mfma_f32_32x32x16_bf16 v[0:15], v[84:87], v[80:83], v[0:15]
	ds_read_b64_tr_b16 v[80:81], v202 offset:16384
	ds_read_b64_tr_b16 v[82:83], v202 offset:18432
	ds_read_b64_tr_b16 v[84:85], v201 offset:20480
	ds_read_b64_tr_b16 v[86:87], v201 offset:22528
	v_fma_f32 v72, v74, s3, -v145
	v_exp_f32_e32 v149, v72
	v_fma_f32 v72, v75, s3, -v145
	v_exp_f32_e32 v197, v72
	s_waitcnt lgkmcnt(4)
	v_mfma_f32_32x32x16_bf16 v[48:63], v[68:71], v[64:67], v[48:63]
	v_fma_f32 v68, v73, s3, -v145
	v_exp_f32_e32 v148, v68
	ds_read_b64_tr_b16 v[68:69], v204 offset:16384
	ds_read_b64_tr_b16 v[70:71], v204 offset:18432
	ds_read_b64_tr_b16 v[88:89], v202 offset:20480
	ds_read_b64_tr_b16 v[90:91], v202 offset:22528
	s_waitcnt lgkmcnt(6)
	v_mfma_f32_32x32x16_bf16 v[32:47], v[80:83], v[64:67], v[32:47]
	ds_read_b64_tr_b16 v[72:73], v206 offset:16384
	ds_read_b64_tr_b16 v[74:75], v206 offset:18432
	ds_read_b64_tr_b16 v[80:81], v204 offset:20480
	ds_read_b64_tr_b16 v[82:83], v204 offset:22528
	s_waitcnt lgkmcnt(2)
	v_mfma_f32_32x32x16_bf16 v[0:15], v[72:75], v[64:67], v[0:15]
	v_add_f32_e32 v74, v205, v203
	v_add_f32_e32 v74, v92, v74
	v_add_f32_e32 v74, v93, v74
	v_add_f32_e32 v74, v94, v74
	v_add_f32_e32 v74, v95, v74
	v_add_f32_e32 v74, v150, v74
	v_add_f32_e32 v74, v151, v74
	v_mfma_f32_32x32x16_bf16 v[16:31], v[68:71], v[64:67], v[16:31]
	v_fma_f32 v68, v76, s3, -v145
	v_add_f32_e32 v74, v152, v74
	v_exp_f32_e32 v76, v68
	v_fma_f32 v68, v77, s3, -v145
	v_fma_f32 v64, v79, s3, -v145
	v_add_f32_e32 v74, v153, v74
	v_exp_f32_e32 v77, v68
	ds_read_b64_tr_b16 v[68:69], v206 offset:20480
	ds_read_b64_tr_b16 v[70:71], v206 offset:22528
	v_exp_f32_e32 v72, v78
	v_exp_f32_e32 v73, v64
	v_add_f32_e32 v74, v194, v74
	v_add_f32_e32 v74, v195, v74
	v_add_f32_e32 v74, v196, v74
	v_add_f32_e32 v74, v146, v74
	v_cvt_pk_bf16_f32 v64, v147, v148
	v_cvt_pk_bf16_f32 v65, v149, v197
	v_cvt_pk_bf16_f32 v66, v76, v77
	v_cvt_pk_bf16_f32 v67, v72, v73
	v_add_f32_e32 v74, v147, v74
	v_add_f32_e32 v74, v148, v74
	v_mfma_f32_32x32x16_bf16 v[48:63], v[84:87], v[64:67], v[48:63]
	v_add_f32_e32 v74, v149, v74
	v_add_f32_e32 v74, v197, v74
	v_add_f32_e32 v74, v76, v74
	v_add_f32_e32 v74, v77, v74
	v_add_f32_e32 v72, v72, v74
	v_add_f32_e32 v72, v73, v72
	v_add_f32_e32 v144, v144, v72
	v_mfma_f32_32x32x16_bf16 v[32:47], v[88:91], v[64:67], v[32:47]
	s_waitcnt lgkmcnt(2)
	v_mfma_f32_32x32x16_bf16 v[16:31], v[80:83], v[64:67], v[16:31]
	s_waitcnt lgkmcnt(0)
	v_mfma_f32_32x32x16_bf16 v[0:15], v[68:71], v[64:67], v[0:15]

.LBB0_206:
	v_cmp_lt_u32_e32 vcc, s8, v119
	s_and_saveexec_b64 s[14:15], vcc
	s_cbranch_execz .LBB0_197
	ds_read_b128 v[220:223], v189 offset:24576
	ds_read_b128 v[68:71], v189 offset:28672
	ds_read_b128 v[224:227], v190 offset:24576
	ds_read_b128 v[132:135], v190 offset:28672
	ds_read_b128 v[228:231], v191 offset:24576
	ds_read_b128 v[136:139], v191 offset:28672
	ds_read_b128 v[232:235], v192 offset:24576
	ds_read_b128 v[140:143], v192 offset:28672
	s_waitcnt lgkmcnt(7)
	v_mfma_f32_32x32x16_bf16 v[80:95], v[220:223], v[96:99], 0
	s_waitcnt lgkmcnt(5)
	v_mfma_f32_32x32x16_bf16 v[80:95], v[224:227], v[100:103], v[80:95]
	s_waitcnt lgkmcnt(3)
	v_mfma_f32_32x32x16_bf16 v[80:95], v[228:231], v[104:107], v[80:95]
	s_waitcnt lgkmcnt(1)
	v_mfma_f32_32x32x16_bf16 v[80:95], v[232:235], v[108:111], v[80:95]
	s_waitcnt lgkmcnt(0)
	v_mfma_f32_32x32x16_bf16 v[64:79], v[68:71], v[96:99], 0
	v_mfma_f32_32x32x16_bf16 v[64:79], v[132:135], v[100:103], v[64:79]
	s_nop 9
	v_max_f32_e32 v132, v81, v81
	v_max_f32_e32 v133, v80, v80
	v_max_f32_e32 v132, v133, v132
	v_max3_f32 v132, v132, v82, v83
	v_max3_f32 v132, v132, v84, v85
	v_max3_f32 v132, v132, v86, v87
	v_max3_f32 v132, v132, v88, v89
	v_mfma_f32_32x32x16_bf16 v[64:79], v[136:139], v[104:107], v[64:79]
	v_max3_f32 v132, v132, v90, v91
	v_max3_f32 v132, v132, v92, v93
	v_max3_f32 v132, v132, v94, v95
	v_mfma_f32_32x32x16_bf16 v[64:79], v[140:143], v[108:111], v[64:79]
	s_nop 11
	v_max3_f32 v132, v132, v64, v65
	v_max3_f32 v132, v132, v66, v67
	v_max3_f32 v132, v132, v68, v69
	v_max3_f32 v132, v132, v70, v71
	v_max3_f32 v132, v132, v72, v73
	v_max3_f32 v132, v132, v74, v75
	v_max3_f32 v132, v132, v76, v77
	v_max3_f32 v132, v132, v78, v79
	v_mov_b32_e32 v133, v132
	s_nop 1
	v_permlane32_swap_b32_e32 v132, v133
	v_max_f32_e32 v132, v132, v133
	v_mul_f32_e32 v132, 0x3e38aa3b, v132
	v_add_f32_e32 v133, 0x41000000, v145
	v_cmp_gt_f32_e32 vcc, v132, v133
	s_cbranch_vccz .LBB0_196
	s_nop 0
	v_cndmask_b32_e32 v133, v145, v132, vcc
	v_sub_f32_e32 v132, v145, v133
	v_exp_f32_e32 v132, v132
	v_mov_b32_e32 v145, v133
	v_pk_mul_f32 v[62:63], v[62:63], v[132:133] op_sel_hi:[1,0]
	v_pk_mul_f32 v[60:61], v[60:61], v[132:133] op_sel_hi:[1,0]
	v_pk_mul_f32 v[58:59], v[58:59], v[132:133] op_sel_hi:[1,0]
	v_pk_mul_f32 v[56:57], v[56:57], v[132:133] op_sel_hi:[1,0]
	v_pk_mul_f32 v[54:55], v[54:55], v[132:133] op_sel_hi:[1,0]
	v_pk_mul_f32 v[52:53], v[52:53], v[132:133] op_sel_hi:[1,0]
	v_pk_mul_f32 v[50:51], v[50:51], v[132:133] op_sel_hi:[1,0]
	v_pk_mul_f32 v[48:49], v[48:49], v[132:133] op_sel_hi:[1,0]
	v_pk_mul_f32 v[46:47], v[46:47], v[132:133] op_sel_hi:[1,0]
	v_pk_mul_f32 v[44:45], v[44:45], v[132:133] op_sel_hi:[1,0]
	v_pk_mul_f32 v[42:43], v[42:43], v[132:133] op_sel_hi:[1,0]
	v_pk_mul_f32 v[40:41], v[40:41], v[132:133] op_sel_hi:[1,0]
	v_pk_mul_f32 v[38:39], v[38:39], v[132:133] op_sel_hi:[1,0]
	v_pk_mul_f32 v[36:37], v[36:37], v[132:133] op_sel_hi:[1,0]
	v_pk_mul_f32 v[34:35], v[34:35], v[132:133] op_sel_hi:[1,0]
	v_pk_mul_f32 v[32:33], v[32:33], v[132:133] op_sel_hi:[1,0]
	v_pk_mul_f32 v[30:31], v[30:31], v[132:133] op_sel_hi:[1,0]
	v_pk_mul_f32 v[28:29], v[28:29], v[132:133] op_sel_hi:[1,0]
	v_pk_mul_f32 v[26:27], v[26:27], v[132:133] op_sel_hi:[1,0]
	v_pk_mul_f32 v[24:25], v[24:25], v[132:133] op_sel_hi:[1,0]
	v_pk_mul_f32 v[22:23], v[22:23], v[132:133] op_sel_hi:[1,0]
	v_pk_mul_f32 v[20:21], v[20:21], v[132:133] op_sel_hi:[1,0]
	v_pk_mul_f32 v[18:19], v[18:19], v[132:133] op_sel_hi:[1,0]
	v_pk_mul_f32 v[16:17], v[16:17], v[132:133] op_sel_hi:[1,0]
	v_pk_mul_f32 v[14:15], v[14:15], v[132:133] op_sel_hi:[1,0]
	v_pk_mul_f32 v[12:13], v[12:13], v[132:133] op_sel_hi:[1,0]
	v_pk_mul_f32 v[10:11], v[10:11], v[132:133] op_sel_hi:[1,0]
	v_pk_mul_f32 v[8:9], v[8:9], v[132:133] op_sel_hi:[1,0]
	v_pk_mul_f32 v[6:7], v[6:7], v[132:133] op_sel_hi:[1,0]
	v_pk_mul_f32 v[4:5], v[4:5], v[132:133] op_sel_hi:[1,0]
	v_pk_mul_f32 v[2:3], v[2:3], v[132:133] op_sel_hi:[1,0]
	v_pk_mul_f32 v[0:1], v[0:1], v[132:133] op_sel_hi:[1,0]
	v_mul_f32_e32 v144, v144, v132
	s_branch .LBB0_196

.LBB0_512:
	v_cmp_le_i32_e32 vcc, s77, v133
	s_and_saveexec_b64 s[54:55], vcc
	s_cbranch_execz .LBB0_515
	v_cmp_gt_f32_e32 vcc, s69, v131
	s_cmp_eq_u64 vcc, exec
	s_cbranch_scc1 .LBB0_515
	v_add_u32_e32 v0, s81, v109
	v_add_u32_e32 v38, v0, v114
	ds_read_b128 v[34:37], v38
	v_add_u32_e32 v42, v0, v115
	ds_read_b128 v[134:137], v42 offset:4096
	ds_read_b128 v[38:41], v38 offset:4096
	v_add_u32_e32 v43, v0, v116
	v_add_u32_e32 v146, v0, v117
	v_add_u32_e32 v0, s79, v132
	v_add_u32_e32 v150, 64, v0
	v_cmp_ne_u32_e32 vcc, s79, v122
	s_waitcnt lgkmcnt(0)
	v_mfma_f32_32x32x16_bf16 v[50:65], v[34:37], v[74:77], 0
	ds_read_b128 v[34:37], v42
	v_add_u32_e32 v151, 0x41, v0
	v_cmp_lt_u32_e64 s[0:1], v150, v130
	v_cmp_lt_u32_e64 s[12:13], v151, v130
	s_or_b64 s[0:1], vcc, s[0:1]
	s_waitcnt lgkmcnt(0)
	v_mfma_f32_32x32x16_bf16 v[50:65], v[34:37], v[66:69], v[50:65]
	ds_read_b128 v[34:37], v43
	ds_read_b128 v[138:141], v43 offset:4096
	ds_read_b128 v[142:145], v146
	ds_read_b128 v[146:149], v146 offset:4096
	s_waitcnt lgkmcnt(0)
	v_mfma_f32_32x32x16_bf16 v[50:65], v[34:37], v[70:73], v[50:65]
	v_mfma_f32_32x32x16_bf16 v[50:65], v[142:145], v[78:81], v[50:65]
	v_mfma_f32_32x32x16_bf16 v[34:49], v[38:41], v[74:77], 0
	s_nop 10
	v_mul_f32_e32 v142, 0x3e000000, v50
	v_mul_f32_e32 v143, 0x3e000000, v51
	v_mul_f32_e64 v50, |v142|, s70
	v_mul_f32_e64 v51, |v143|, s70
	v_exp_f32_e32 v50, v50
	v_exp_f32_e32 v51, v51
	v_add_f32_e32 v50, 1.0, v50
	v_mfma_f32_32x32x16_bf16 v[34:49], v[134:137], v[66:69], v[34:49]
	v_add_f32_e32 v51, 1.0, v51
	v_cmp_gt_f32_e64 s[16:17], s71, v50
	v_cmp_gt_f32_e64 s[18:19], s71, v51
	v_max_f32_e32 v135, 0, v143
	v_cndmask_b32_e64 v136, 0, 32, s[16:17]
	v_cndmask_b32_e64 v137, 0, 32, s[18:19]
	v_ldexp_f32 v50, v50, v136
	v_ldexp_f32 v51, v51, v137
	v_log_f32_e32 v50, v50
	v_log_f32_e32 v51, v51
	v_mfma_f32_32x32x16_bf16 v[34:49], v[138:141], v[70:73], v[34:49]
	v_cndmask_b32_e64 v136, 0, v128, s[16:17]
	v_mul_f32_e32 v138, 0x3f317217, v50
	v_mul_f32_e32 v139, 0x3f317217, v51
	v_fma_f32 v138, v50, s72, -v138
	v_fma_f32 v139, v51, s72, -v139
	v_fmac_f32_e32 v138, 0x3377d1cf, v50
	v_fmac_f32_e32 v139, 0x3377d1cf, v51
	v_fmac_f32_e32 v138, 0x3f317217, v50
	v_cmp_lt_f32_e64 s[16:17], |v50|, s73
	v_fmac_f32_e32 v139, 0x3f317217, v51
	v_cndmask_b32_e64 v137, 0, v128, s[18:19]
	v_cndmask_b32_e64 v50, v50, v138, s[16:17]
	v_cmp_lt_f32_e64 s[16:17], |v51|, s73
	v_sub_f32_e32 v50, v50, v136
	v_max_f32_e32 v134, 0, v142
	v_cndmask_b32_e64 v138, v51, v139, s[16:17]
	v_sub_f32_e32 v136, v138, v137
	v_add_f32_e32 v135, v135, v136
	v_mul_f32_e32 v136, 0x3e000000, v52
	v_mul_f32_e64 v52, |v136|, s70
	v_exp_f32_e32 v137, v52
	v_add_f32_e32 v50, v134, v50
	v_cndmask_b32_e64 v50, 0, -v50, s[0:1]
	v_cndmask_b32_e64 v51, v129, v142, s[0:1]
	s_or_b64 s[0:1], vcc, s[12:13]
	v_add_f32_e32 v134, 0, v50
	v_cndmask_b32_e64 v52, 0, -v135, s[0:1]
	v_add_f32_e32 v137, 1.0, v137
	v_add_f32_e32 v135, v52, v134
	v_cndmask_b32_e64 v134, v129, v143, s[0:1]
	v_cmp_gt_f32_e64 s[0:1], s71, v137
	v_mfma_f32_32x32x16_bf16 v[34:49], v[146:149], v[78:81], v[34:49]
	s_nop 0
	v_cndmask_b32_e64 v138, 0, 32, s[0:1]
	v_ldexp_f32 v137, v137, v138
	v_log_f32_e32 v137, v137
	v_add_u32_e32 v138, 0x42, v0
	v_cmp_lt_u32_e64 s[12:13], v138, v130
	v_max_f32_e32 v138, 0, v136
	v_mul_f32_e32 v139, 0x3f317217, v137
	v_fma_f32 v139, v137, s72, -v139
	v_fmac_f32_e32 v139, 0x3377d1cf, v137
	v_fmac_f32_e32 v139, 0x3f317217, v137
	v_cmp_lt_f32_e64 s[16:17], |v137|, s73
	v_mul_f32_e32 v38, 0x3e000000, v38
	v_mul_f32_e32 v39, 0x3e000000, v39
	v_cndmask_b32_e64 v137, v137, v139, s[16:17]
	v_cndmask_b32_e64 v139, 0, v128, s[0:1]
	v_sub_f32_e32 v137, v137, v139
	v_mul_f32_e32 v139, 0x3e000000, v53
	v_mul_f32_e64 v53, |v139|, s70
	v_add_f32_e32 v137, v138, v137
	v_exp_f32_e32 v138, v53
	s_or_b64 s[0:1], vcc, s[12:13]
	v_cndmask_b32_e64 v53, 0, -v137, s[0:1]
	v_add_f32_e32 v137, v53, v135
	v_cndmask_b32_e64 v135, v129, v136, s[0:1]
	v_add_f32_e32 v136, 1.0, v138
	v_cmp_gt_f32_e64 s[0:1], s71, v136
	v_mul_f32_e32 v40, 0x3e000000, v40
	v_mul_f32_e32 v41, 0x3e000000, v41
	v_cndmask_b32_e64 v138, 0, 32, s[0:1]
	v_ldexp_f32 v136, v136, v138
	v_log_f32_e32 v136, v136
	v_add_u32_e32 v138, 0x43, v0
	v_cmp_lt_u32_e64 s[12:13], v138, v130
	v_max_f32_e32 v138, 0, v139
	v_mul_f32_e32 v140, 0x3f317217, v136
	v_fma_f32 v140, v136, s72, -v140
	v_fmac_f32_e32 v140, 0x3377d1cf, v136
	v_fmac_f32_e32 v140, 0x3f317217, v136
	v_cmp_lt_f32_e64 s[16:17], |v136|, s73
	s_nop 1
	v_cndmask_b32_e64 v136, v136, v140, s[16:17]
	v_cndmask_b32_e64 v140, 0, v128, s[0:1]
	v_sub_f32_e32 v136, v136, v140
	v_mul_f32_e32 v140, 0x3e000000, v54
	v_mul_f32_e64 v54, |v140|, s70
	v_exp_f32_e32 v141, v54
	v_add_f32_e32 v136, v138, v136
	s_or_b64 s[0:1], vcc, s[12:13]
	v_cndmask_b32_e64 v54, 0, -v136, s[0:1]
	v_add_f32_e32 v138, v54, v137
	v_add_f32_e32 v137, 1.0, v141
	v_cndmask_b32_e64 v136, v129, v139, s[0:1]
	v_cmp_gt_f32_e64 s[0:1], s71, v137
	s_nop 1
	v_cndmask_b32_e64 v139, 0, 32, s[0:1]
	v_ldexp_f32 v137, v137, v139
	v_log_f32_e32 v137, v137
	v_add_u32_e32 v139, 0x48, v0
	v_cmp_lt_u32_e64 s[12:13], v139, v130
	v_max_f32_e32 v139, 0, v140
	v_mul_f32_e32 v141, 0x3f317217, v137
	v_fma_f32 v141, v137, s72, -v141
	v_fmac_f32_e32 v141, 0x3377d1cf, v137
	v_fmac_f32_e32 v141, 0x3f317217, v137
	v_cmp_lt_f32_e64 s[16:17], |v137|, s73
	s_nop 1
	v_cndmask_b32_e64 v137, v137, v141, s[16:17]
	v_cndmask_b32_e64 v141, 0, v128, s[0:1]
	v_sub_f32_e32 v137, v137, v141
	v_add_f32_e32 v137, v139, v137
	v_mul_f32_e32 v139, 0x3e000000, v55
	v_mul_f32_e64 v55, |v139|, s70
	v_exp_f32_e32 v141, v55
	s_or_b64 s[0:1], vcc, s[12:13]
	v_cndmask_b32_e64 v55, 0, -v137, s[0:1]
	v_cndmask_b32_e64 v137, v129, v140, s[0:1]
	v_add_f32_e32 v140, 1.0, v141
	v_cmp_gt_f32_e64 s[0:1], s71, v140
	v_add_f32_e32 v142, 0, v55
	s_nop 0
	v_cndmask_b32_e64 v141, 0, 32, s[0:1]
	v_ldexp_f32 v140, v140, v141
	v_log_f32_e32 v140, v140
	v_add_u32_e32 v141, 0x49, v0
	v_cmp_lt_u32_e64 s[12:13], v141, v130
	v_max_f32_e32 v141, 0, v139
	v_mul_f32_e32 v143, 0x3f317217, v140
	v_fma_f32 v143, v140, s72, -v143
	v_fmac_f32_e32 v143, 0x3377d1cf, v140
	v_fmac_f32_e32 v143, 0x3f317217, v140
	v_cmp_lt_f32_e64 s[16:17], |v140|, s73
	s_nop 1
	v_cndmask_b32_e64 v140, v140, v143, s[16:17]
	v_cndmask_b32_e64 v143, 0, v128, s[0:1]
	v_sub_f32_e32 v140, v140, v143
	v_add_f32_e32 v140, v141, v140
	v_mul_f32_e32 v141, 0x3e000000, v56
	v_mul_f32_e64 v56, |v141|, s70
	v_exp_f32_e32 v143, v56
	s_or_b64 s[0:1], vcc, s[12:13]
	v_cndmask_b32_e64 v56, 0, -v140, s[0:1]
	v_add_f32_e32 v140, v56, v142
	v_add_f32_e32 v142, 1.0, v143
	v_cndmask_b32_e64 v139, v129, v139, s[0:1]
	v_cmp_gt_f32_e64 s[0:1], s71, v142
	s_nop 1
	v_cndmask_b32_e64 v143, 0, 32, s[0:1]
	v_ldexp_f32 v142, v142, v143
	v_log_f32_e32 v142, v142
	v_add_u32_e32 v143, 0x4a, v0
	v_cmp_lt_u32_e64 s[12:13], v143, v130
	v_max_f32_e32 v143, 0, v141
	v_mul_f32_e32 v144, 0x3f317217, v142
	v_fma_f32 v144, v142, s72, -v144
	v_fmac_f32_e32 v144, 0x3377d1cf, v142
	v_fmac_f32_e32 v144, 0x3f317217, v142
	v_cmp_lt_f32_e64 s[16:17], |v142|, s73
	s_nop 1
	v_cndmask_b32_e64 v142, v142, v144, s[16:17]
	v_cndmask_b32_e64 v144, 0, v128, s[0:1]
	v_sub_f32_e32 v142, v142, v144
	v_mul_f32_e32 v144, 0x3e000000, v57
	v_mul_f32_e64 v57, |v144|, s70
	v_add_f32_e32 v142, v143, v142
	v_exp_f32_e32 v143, v57
	s_or_b64 s[0:1], vcc, s[12:13]
	v_cndmask_b32_e64 v57, 0, -v142, s[0:1]
	v_add_f32_e32 v142, v57, v140
	v_cndmask_b32_e64 v140, v129, v141, s[0:1]
	v_add_f32_e32 v141, 1.0, v143
	v_cmp_gt_f32_e64 s[0:1], s71, v141
	s_nop 1
	v_cndmask_b32_e64 v143, 0, 32, s[0:1]
	v_ldexp_f32 v141, v141, v143
	v_log_f32_e32 v141, v141
	v_add_u32_e32 v143, 0x4b, v0
	v_cmp_lt_u32_e64 s[12:13], v143, v130
	v_max_f32_e32 v143, 0, v144
	v_mul_f32_e32 v145, 0x3f317217, v141
	v_fma_f32 v145, v141, s72, -v145
	v_fmac_f32_e32 v145, 0x3377d1cf, v141
	v_fmac_f32_e32 v145, 0x3f317217, v141
	v_cmp_lt_f32_e64 s[16:17], |v141|, s73
	s_nop 1
	v_cndmask_b32_e64 v141, v141, v145, s[16:17]
	v_cndmask_b32_e64 v145, 0, v128, s[0:1]
	v_sub_f32_e32 v141, v141, v145
	v_mul_f32_e32 v145, 0x3e000000, v58
	v_mul_f32_e64 v58, |v145|, s70
	v_exp_f32_e32 v146, v58
	v_add_f32_e32 v141, v143, v141
	s_or_b64 s[0:1], vcc, s[12:13]
	v_cndmask_b32_e64 v58, 0, -v141, s[0:1]
	v_add_f32_e32 v143, v58, v142
	v_add_f32_e32 v142, 1.0, v146
	v_cndmask_b32_e64 v141, v129, v144, s[0:1]
	v_cmp_gt_f32_e64 s[0:1], s71, v142
	s_nop 1
	v_cndmask_b32_e64 v144, 0, 32, s[0:1]
	v_ldexp_f32 v142, v142, v144
	v_log_f32_e32 v142, v142
	v_add_u32_e32 v144, 0x50, v0
	v_cmp_lt_u32_e64 s[12:13], v144, v130
	v_max_f32_e32 v144, 0, v145
	v_mul_f32_e32 v146, 0x3f317217, v142
	v_fma_f32 v146, v142, s72, -v146
	v_fmac_f32_e32 v146, 0x3377d1cf, v142
	v_fmac_f32_e32 v146, 0x3f317217, v142
	v_cmp_lt_f32_e64 s[16:17], |v142|, s73
	s_nop 1
	v_cndmask_b32_e64 v142, v142, v146, s[16:17]
	v_cndmask_b32_e64 v146, 0, v128, s[0:1]
	v_sub_f32_e32 v142, v142, v146
	v_add_f32_e32 v142, v144, v142
	v_mul_f32_e32 v144, 0x3e000000, v59
	v_mul_f32_e64 v59, |v144|, s70
	v_exp_f32_e32 v146, v59
	s_or_b64 s[0:1], vcc, s[12:13]
	v_cndmask_b32_e64 v59, 0, -v142, s[0:1]
	v_cndmask_b32_e64 v142, v129, v145, s[0:1]
	v_add_f32_e32 v145, 1.0, v146
	v_cmp_gt_f32_e64 s[0:1], s71, v145
	v_add_f32_e32 v147, 0, v59
	s_nop 0
	v_cndmask_b32_e64 v146, 0, 32, s[0:1]
	v_ldexp_f32 v145, v145, v146
	v_log_f32_e32 v145, v145
	v_add_u32_e32 v146, 0x51, v0
	v_cmp_lt_u32_e64 s[12:13], v146, v130
	v_max_f32_e32 v146, 0, v144
	v_mul_f32_e32 v148, 0x3f317217, v145
	v_fma_f32 v148, v145, s72, -v148
	v_fmac_f32_e32 v148, 0x3377d1cf, v145
	v_fmac_f32_e32 v148, 0x3f317217, v145
	v_cmp_lt_f32_e64 s[16:17], |v145|, s73
	s_nop 1
	v_cndmask_b32_e64 v145, v145, v148, s[16:17]
	v_cndmask_b32_e64 v148, 0, v128, s[0:1]
	v_sub_f32_e32 v145, v145, v148
	v_add_f32_e32 v145, v146, v145
	v_mul_f32_e32 v146, 0x3e000000, v60
	v_mul_f32_e64 v60, |v146|, s70
	v_exp_f32_e32 v148, v60
	s_or_b64 s[0:1], vcc, s[12:13]
	v_cndmask_b32_e64 v60, 0, -v145, s[0:1]
	v_add_f32_e32 v145, v60, v147
	v_add_f32_e32 v147, 1.0, v148
	v_cndmask_b32_e64 v144, v129, v144, s[0:1]
	v_cmp_gt_f32_e64 s[0:1], s71, v147
	s_nop 1
	v_cndmask_b32_e64 v148, 0, 32, s[0:1]
	v_ldexp_f32 v147, v147, v148
	v_log_f32_e32 v147, v147
	v_add_u32_e32 v148, 0x52, v0
	v_cmp_lt_u32_e64 s[12:13], v148, v130
	v_max_f32_e32 v148, 0, v146
	v_mul_f32_e32 v149, 0x3f317217, v147
	v_fma_f32 v149, v147, s72, -v149
	v_fmac_f32_e32 v149, 0x3377d1cf, v147
	v_fmac_f32_e32 v149, 0x3f317217, v147
	v_cmp_lt_f32_e64 s[16:17], |v147|, s73
	s_nop 1
	v_cndmask_b32_e64 v147, v147, v149, s[16:17]
	v_cndmask_b32_e64 v149, 0, v128, s[0:1]
	v_sub_f32_e32 v147, v147, v149
	v_mul_f32_e32 v149, 0x3e000000, v61
	v_mul_f32_e64 v61, |v149|, s70
	v_add_f32_e32 v147, v148, v147
	v_exp_f32_e32 v148, v61
	s_or_b64 s[0:1], vcc, s[12:13]
	v_cndmask_b32_e64 v61, 0, -v147, s[0:1]
	v_add_f32_e32 v147, v61, v145
	v_cndmask_b32_e64 v145, v129, v146, s[0:1]
	v_add_f32_e32 v146, 1.0, v148
	v_cmp_gt_f32_e64 s[0:1], s71, v146
	s_nop 1
	v_cndmask_b32_e64 v148, 0, 32, s[0:1]
	v_ldexp_f32 v146, v146, v148
	v_log_f32_e32 v146, v146
	v_add_u32_e32 v148, 0x53, v0
	v_cmp_lt_u32_e64 s[12:13], v148, v130
	v_max_f32_e32 v148, 0, v149
	v_mul_f32_e32 v150, 0x3f317217, v146
	v_fma_f32 v150, v146, s72, -v150
	v_fmac_f32_e32 v150, 0x3377d1cf, v146
	v_fmac_f32_e32 v150, 0x3f317217, v146
	v_cmp_lt_f32_e64 s[16:17], |v146|, s73
	s_nop 1
	v_cndmask_b32_e64 v146, v146, v150, s[16:17]
	v_cndmask_b32_e64 v150, 0, v128, s[0:1]
	v_sub_f32_e32 v146, v146, v150
	v_mul_f32_e32 v150, 0x3e000000, v62
	v_mul_f32_e64 v62, |v150|, s70
	v_exp_f32_e32 v151, v62
	v_add_f32_e32 v146, v148, v146
	s_or_b64 s[0:1], vcc, s[12:13]
	v_cndmask_b32_e64 v62, 0, -v146, s[0:1]
	v_add_f32_e32 v148, v62, v147
	v_add_f32_e32 v147, 1.0, v151
	v_cndmask_b32_e64 v146, v129, v149, s[0:1]
	v_cmp_gt_f32_e64 s[0:1], s71, v147
	s_nop 1
	v_cndmask_b32_e64 v149, 0, 32, s[0:1]
	v_ldexp_f32 v147, v147, v149
	v_log_f32_e32 v147, v147
	v_add_u32_e32 v149, 0x58, v0
	v_cmp_lt_u32_e64 s[12:13], v149, v130
	v_max_f32_e32 v149, 0, v150
	v_mul_f32_e32 v151, 0x3f317217, v147
	v_fma_f32 v151, v147, s72, -v151
	v_fmac_f32_e32 v151, 0x3377d1cf, v147
	v_fmac_f32_e32 v151, 0x3f317217, v147
	v_cmp_lt_f32_e64 s[16:17], |v147|, s73
	s_nop 1
	v_cndmask_b32_e64 v147, v147, v151, s[16:17]
	v_cndmask_b32_e64 v151, 0, v128, s[0:1]
	v_sub_f32_e32 v147, v147, v151
	v_add_f32_e32 v147, v149, v147
	v_mul_f32_e32 v149, 0x3e000000, v63
	v_mul_f32_e64 v63, |v149|, s70
	v_exp_f32_e32 v151, v63
	s_or_b64 s[0:1], vcc, s[12:13]
	v_cndmask_b32_e64 v63, 0, -v147, s[0:1]
	v_cndmask_b32_e64 v147, v129, v150, s[0:1]
	v_add_f32_e32 v150, 1.0, v151
	v_cmp_gt_f32_e64 s[0:1], s71, v150
	v_add_f32_e32 v152, 0, v63
	s_nop 0
	v_cndmask_b32_e64 v151, 0, 32, s[0:1]
	v_ldexp_f32 v150, v150, v151
	v_log_f32_e32 v150, v150
	v_add_u32_e32 v151, 0x59, v0
	v_cmp_lt_u32_e64 s[12:13], v151, v130
	v_max_f32_e32 v151, 0, v149
	v_mul_f32_e32 v153, 0x3f317217, v150
	v_fma_f32 v153, v150, s72, -v153
	v_fmac_f32_e32 v153, 0x3377d1cf, v150
	v_fmac_f32_e32 v153, 0x3f317217, v150
	v_cmp_lt_f32_e64 s[16:17], |v150|, s73
	s_nop 1
	v_cndmask_b32_e64 v150, v150, v153, s[16:17]
	v_cndmask_b32_e64 v153, 0, v128, s[0:1]
	v_sub_f32_e32 v150, v150, v153
	v_add_f32_e32 v150, v151, v150
	v_mul_f32_e32 v151, 0x3e000000, v64
	v_mul_f32_e64 v64, |v151|, s70
	v_exp_f32_e32 v153, v64
	s_or_b64 s[0:1], vcc, s[12:13]
	v_cndmask_b32_e64 v64, 0, -v150, s[0:1]
	v_add_f32_e32 v150, v64, v152
	v_add_f32_e32 v152, 1.0, v153
	v_cndmask_b32_e64 v149, v129, v149, s[0:1]
	v_cmp_gt_f32_e64 s[0:1], s71, v152
	s_nop 1
	v_cndmask_b32_e64 v153, 0, 32, s[0:1]
	v_ldexp_f32 v152, v152, v153
	v_log_f32_e32 v152, v152
	v_add_u32_e32 v153, 0x5a, v0
	v_cmp_lt_u32_e64 s[12:13], v153, v130
	v_max_f32_e32 v153, 0, v151
	v_mul_f32_e32 v155, 0x3f317217, v152
	v_fma_f32 v155, v152, s72, -v155
	v_fmac_f32_e32 v155, 0x3377d1cf, v152
	v_fmac_f32_e32 v155, 0x3f317217, v152
	v_cmp_lt_f32_e64 s[16:17], |v152|, s73
	s_nop 1
	v_cndmask_b32_e64 v152, v152, v155, s[16:17]
	v_cndmask_b32_e64 v155, 0, v128, s[0:1]
	v_sub_f32_e32 v152, v152, v155
	v_mul_f32_e32 v155, 0x3e000000, v65
	v_mul_f32_e64 v65, |v155|, s70
	v_add_f32_e32 v152, v153, v152
	v_exp_f32_e32 v153, v65
	s_or_b64 s[0:1], vcc, s[12:13]
	v_cndmask_b32_e64 v65, 0, -v152, s[0:1]
	v_add_f32_e32 v152, v65, v150
	v_cndmask_b32_e64 v150, v129, v151, s[0:1]
	v_add_f32_e32 v151, 1.0, v153
	v_cmp_gt_f32_e64 s[0:1], s71, v151
	s_nop 1
	v_cndmask_b32_e64 v153, 0, 32, s[0:1]
	v_ldexp_f32 v151, v151, v153
	v_log_f32_e32 v151, v151
	v_add_u32_e32 v153, 0x5b, v0
	v_cmp_lt_u32_e64 s[12:13], v153, v130
	v_max_f32_e32 v153, 0, v155
	v_mul_f32_e32 v156, 0x3f317217, v151
	v_fma_f32 v156, v151, s72, -v156
	v_fmac_f32_e32 v156, 0x3377d1cf, v151
	v_fmac_f32_e32 v156, 0x3f317217, v151
	v_cmp_lt_f32_e64 s[16:17], |v151|, s73
	s_nop 1
	v_cndmask_b32_e64 v151, v151, v156, s[16:17]
	v_cndmask_b32_e64 v156, 0, v128, s[0:1]
	v_sub_f32_e32 v151, v151, v156
	v_mul_f32_e32 v156, 0x3e000000, v34
	v_mul_f32_e64 v34, |v156|, s70
	v_exp_f32_e32 v34, v34
	v_add_f32_e32 v151, v153, v151
	s_or_b64 s[0:1], vcc, s[12:13]
	v_cndmask_b32_e64 v151, 0, -v151, s[0:1]
	v_add_f32_e32 v34, 1.0, v34
	v_add_f32_e32 v153, v151, v152
	v_cndmask_b32_e64 v152, v129, v155, s[0:1]
	v_cmp_gt_f32_e64 s[0:1], s71, v34
	s_nop 1
	v_cndmask_b32_e64 v155, 0, 32, s[0:1]
	v_ldexp_f32 v34, v34, v155
	v_log_f32_e32 v34, v34
	v_add_u32_e32 v155, 0x60, v0
	v_cmp_lt_u32_e64 s[12:13], v155, v130
	v_max_f32_e32 v155, 0, v156
	v_mul_f32_e32 v157, 0x3f317217, v34
	v_fma_f32 v157, v34, s72, -v157
	v_fmac_f32_e32 v157, 0x3377d1cf, v34
	v_fmac_f32_e32 v157, 0x3f317217, v34
	v_cmp_lt_f32_e64 s[16:17], |v34|, s73
	s_nop 1
	v_cndmask_b32_e64 v34, v34, v157, s[16:17]
	v_cndmask_b32_e64 v157, 0, v128, s[0:1]
	v_sub_f32_e32 v34, v34, v157
	v_add_f32_e32 v34, v155, v34
	v_mul_f32_e32 v155, 0x3e000000, v35
	v_mul_f32_e64 v35, |v155|, s70
	v_exp_f32_e32 v157, v35
	s_or_b64 s[0:1], vcc, s[12:13]
	v_cndmask_b32_e64 v35, v129, v156, s[0:1]
	v_cndmask_b32_e64 v34, 0, -v34, s[0:1]
	v_add_f32_e32 v156, 1.0, v157
	v_cmp_gt_f32_e64 s[0:1], s71, v156
	v_add_f32_e32 v158, 0, v34
	s_nop 0
	v_cndmask_b32_e64 v157, 0, 32, s[0:1]
	v_ldexp_f32 v156, v156, v157
	v_log_f32_e32 v156, v156
	v_add_u32_e32 v157, 0x61, v0
	v_cmp_lt_u32_e64 s[12:13], v157, v130
	v_max_f32_e32 v157, 0, v155
	v_mul_f32_e32 v159, 0x3f317217, v156
	v_fma_f32 v159, v156, s72, -v159
	v_fmac_f32_e32 v159, 0x3377d1cf, v156
	v_fmac_f32_e32 v159, 0x3f317217, v156
	v_cmp_lt_f32_e64 s[16:17], |v156|, s73
	s_nop 1
	v_cndmask_b32_e64 v156, v156, v159, s[16:17]
	v_cndmask_b32_e64 v159, 0, v128, s[0:1]
	v_sub_f32_e32 v156, v156, v159
	v_add_f32_e32 v156, v157, v156
	v_mul_f32_e32 v157, 0x3e000000, v36
	v_mul_f32_e64 v36, |v157|, s70
	v_exp_f32_e32 v159, v36
	s_or_b64 s[0:1], vcc, s[12:13]
	v_cndmask_b32_e64 v36, 0, -v156, s[0:1]
	v_add_f32_e32 v156, v36, v158
	v_add_f32_e32 v158, 1.0, v159
	v_cndmask_b32_e64 v155, v129, v155, s[0:1]
	v_cmp_gt_f32_e64 s[0:1], s71, v158
	s_nop 1
	v_cndmask_b32_e64 v159, 0, 32, s[0:1]
	v_ldexp_f32 v158, v158, v159
	v_log_f32_e32 v158, v158
	v_add_u32_e32 v159, 0x62, v0
	v_cmp_lt_u32_e64 s[12:13], v159, v130
	v_max_f32_e32 v159, 0, v157
	v_mul_f32_e32 v160, 0x3f317217, v158
	v_fma_f32 v160, v158, s72, -v160
	v_fmac_f32_e32 v160, 0x3377d1cf, v158
	v_fmac_f32_e32 v160, 0x3f317217, v158
	v_cmp_lt_f32_e64 s[16:17], |v158|, s73
	s_nop 1
	v_cndmask_b32_e64 v158, v158, v160, s[16:17]
	v_cndmask_b32_e64 v160, 0, v128, s[0:1]
	v_sub_f32_e32 v158, v158, v160
	v_add_f32_e32 v158, v159, v158
	v_mul_f32_e32 v159, 0x3e000000, v37
	v_mul_f32_e64 v37, |v159|, s70
	v_exp_f32_e32 v160, v37
	s_or_b64 s[0:1], vcc, s[12:13]
	v_cndmask_b32_e64 v37, 0, -v158, s[0:1]
	v_add_f32_e32 v158, v37, v156
	v_cndmask_b32_e64 v156, v129, v157, s[0:1]
	v_add_f32_e32 v157, 1.0, v160
	v_cmp_gt_f32_e64 s[0:1], s71, v157
	s_nop 1
	v_cndmask_b32_e64 v160, 0, 32, s[0:1]
	v_ldexp_f32 v157, v157, v160
	v_log_f32_e32 v157, v157
	v_add_u32_e32 v160, 0x63, v0
	v_cmp_lt_u32_e64 s[12:13], v160, v130
	v_max_f32_e32 v160, 0, v159
	v_mul_f32_e32 v161, 0x3f317217, v157
	v_fma_f32 v161, v157, s72, -v161
	v_fmac_f32_e32 v161, 0x3377d1cf, v157
	v_fmac_f32_e32 v161, 0x3f317217, v157
	v_cmp_lt_f32_e64 s[16:17], |v157|, s73
	s_nop 1
	v_cndmask_b32_e64 v157, v157, v161, s[16:17]
	v_cndmask_b32_e64 v161, 0, v128, s[0:1]
	v_sub_f32_e32 v157, v157, v161
	v_add_f32_e32 v157, v160, v157
	v_mul_f32_e64 v160, |v38|, s70
	v_exp_f32_e32 v160, v160
	s_or_b64 s[0:1], vcc, s[12:13]
	v_cndmask_b32_e64 v157, 0, -v157, s[0:1]
	v_cndmask_b32_e64 v159, v129, v159, s[0:1]
	v_add_f32_e32 v160, 1.0, v160
	v_cmp_gt_f32_e64 s[0:1], s71, v160
	v_add_f32_e32 v158, v157, v158
	s_nop 0
	v_cndmask_b32_e64 v161, 0, 32, s[0:1]
	v_ldexp_f32 v160, v160, v161
	v_log_f32_e32 v160, v160
	v_add_u32_e32 v161, 0x68, v0
	v_cmp_lt_u32_e64 s[12:13], v161, v130
	v_max_f32_e32 v161, 0, v38
	v_mul_f32_e32 v162, 0x3f317217, v160
	v_fma_f32 v162, v160, s72, -v162
	v_fmac_f32_e32 v162, 0x3377d1cf, v160
	v_fmac_f32_e32 v162, 0x3f317217, v160
	v_cmp_lt_f32_e64 s[16:17], |v160|, s73
	s_nop 1
	v_cndmask_b32_e64 v160, v160, v162, s[16:17]
	v_cndmask_b32_e64 v162, 0, v128, s[0:1]
	v_sub_f32_e32 v160, v160, v162
	v_add_f32_e32 v160, v161, v160
	v_mul_f32_e64 v161, |v39|, s70
	v_exp_f32_e32 v161, v161
	s_or_b64 s[0:1], vcc, s[12:13]
	v_cndmask_b32_e64 v163, v129, v38, s[0:1]
	v_cndmask_b32_e64 v160, 0, -v160, s[0:1]
	v_add_f32_e32 v38, 1.0, v161
	v_cmp_gt_f32_e64 s[0:1], s71, v38
	v_add_f32_e32 v162, 0, v160
	s_nop 0
	v_cndmask_b32_e64 v161, 0, 32, s[0:1]
	v_ldexp_f32 v38, v38, v161
	v_log_f32_e32 v38, v38
	v_add_u32_e32 v161, 0x69, v0
	v_cmp_lt_u32_e64 s[12:13], v161, v130
	v_max_f32_e32 v161, 0, v39
	v_mul_f32_e32 v164, 0x3f317217, v38
	v_fma_f32 v164, v38, s72, -v164
	v_fmac_f32_e32 v164, 0x3377d1cf, v38
	v_fmac_f32_e32 v164, 0x3f317217, v38
	v_cmp_lt_f32_e64 s[16:17], |v38|, s73
	s_nop 1
	v_cndmask_b32_e64 v38, v38, v164, s[16:17]
	v_cndmask_b32_e64 v164, 0, v128, s[0:1]
	v_sub_f32_e32 v38, v38, v164
	v_add_f32_e32 v38, v161, v38
	v_mul_f32_e64 v161, |v40|, s70
	v_exp_f32_e32 v161, v161
	s_or_b64 s[0:1], vcc, s[12:13]
	v_cndmask_b32_e64 v164, 0, -v38, s[0:1]
	v_add_f32_e32 v38, v164, v162
	v_cndmask_b32_e64 v162, v129, v39, s[0:1]
	v_add_f32_e32 v39, 1.0, v161
	v_cmp_gt_f32_e64 s[0:1], s71, v39
	s_nop 1
	v_cndmask_b32_e64 v161, 0, 32, s[0:1]
	v_ldexp_f32 v39, v39, v161
	v_log_f32_e32 v39, v39
	v_add_u32_e32 v161, 0x6a, v0
	v_cmp_lt_u32_e64 s[12:13], v161, v130
	v_max_f32_e32 v161, 0, v40
	v_mul_f32_e32 v165, 0x3f317217, v39
	v_fma_f32 v165, v39, s72, -v165
	v_fmac_f32_e32 v165, 0x3377d1cf, v39
	v_fmac_f32_e32 v165, 0x3f317217, v39
	v_cmp_lt_f32_e64 s[16:17], |v39|, s73
	s_nop 1
	v_cndmask_b32_e64 v39, v39, v165, s[16:17]
	v_cndmask_b32_e64 v165, 0, v128, s[0:1]
	v_sub_f32_e32 v39, v39, v165
	v_add_f32_e32 v39, v161, v39
	v_mul_f32_e64 v161, |v41|, s70
	v_exp_f32_e32 v161, v161
	s_or_b64 s[0:1], vcc, s[12:13]
	v_cndmask_b32_e64 v165, 0, -v39, s[0:1]
	v_cndmask_b32_e64 v166, v129, v40, s[0:1]
	v_add_f32_e32 v39, 1.0, v161
	v_cmp_gt_f32_e64 s[0:1], s71, v39
	v_add_f32_e32 v38, v165, v38
	s_nop 0
	v_cndmask_b32_e64 v40, 0, 32, s[0:1]
	v_ldexp_f32 v39, v39, v40
	v_log_f32_e32 v39, v39
	v_add_u32_e32 v40, 0x6b, v0
	v_cmp_lt_u32_e64 s[12:13], v40, v130
	v_max_f32_e32 v40, 0, v41
	v_mul_f32_e32 v161, 0x3f317217, v39
	v_fma_f32 v161, v39, s72, -v161
	v_fmac_f32_e32 v161, 0x3377d1cf, v39
	v_fmac_f32_e32 v161, 0x3f317217, v39
	v_cmp_lt_f32_e64 s[16:17], |v39|, s73
	s_nop 1
	v_cndmask_b32_e64 v39, v39, v161, s[16:17]
	v_cndmask_b32_e64 v161, 0, v128, s[0:1]
	v_sub_f32_e32 v39, v39, v161
	v_add_f32_e32 v39, v40, v39
	v_mul_f32_e32 v40, 0x3e000000, v42
	v_mul_f32_e64 v42, |v40|, s70
	v_exp_f32_e32 v42, v42
	s_or_b64 s[0:1], vcc, s[12:13]
	v_cndmask_b32_e64 v161, 0, -v39, s[0:1]
	v_add_f32_e32 v167, v161, v38
	v_add_f32_e32 v38, 1.0, v42
	v_cndmask_b32_e64 v168, v129, v41, s[0:1]
	v_cmp_gt_f32_e64 s[0:1], s71, v38
	s_nop 1
	v_cndmask_b32_e64 v39, 0, 32, s[0:1]
	v_ldexp_f32 v38, v38, v39
	v_log_f32_e32 v38, v38
	v_add_u32_e32 v39, 0x70, v0
	v_cmp_lt_u32_e64 s[12:13], v39, v130
	v_max_f32_e32 v39, 0, v40
	v_mul_f32_e32 v41, 0x3f317217, v38
	v_fma_f32 v41, v38, s72, -v41
	v_fmac_f32_e32 v41, 0x3377d1cf, v38
	v_fmac_f32_e32 v41, 0x3f317217, v38
	v_cmp_lt_f32_e64 s[16:17], |v38|, s73
	s_nop 1
	v_cndmask_b32_e64 v38, v38, v41, s[16:17]
	v_cndmask_b32_e64 v41, 0, v128, s[0:1]
	v_sub_f32_e32 v38, v38, v41
	v_add_f32_e32 v38, v39, v38
	v_mul_f32_e32 v39, 0x3e000000, v43
	v_mul_f32_e64 v41, |v39|, s70
	v_exp_f32_e32 v41, v41
	s_or_b64 s[0:1], vcc, s[12:13]
	v_cndmask_b32_e64 v170, v129, v40, s[0:1]
	v_cndmask_b32_e64 v169, 0, -v38, s[0:1]
	v_add_f32_e32 v40, 1.0, v41
	v_cmp_gt_f32_e64 s[0:1], s71, v40
	v_add_f32_e32 v38, 0, v169
	s_nop 0
	v_cndmask_b32_e64 v41, 0, 32, s[0:1]
	v_ldexp_f32 v40, v40, v41
	v_log_f32_e32 v40, v40
	v_add_u32_e32 v41, 0x71, v0
	v_cmp_lt_u32_e64 s[12:13], v41, v130
	v_max_f32_e32 v41, 0, v39
	v_mul_f32_e32 v42, 0x3f317217, v40
	v_fma_f32 v42, v40, s72, -v42
	v_fmac_f32_e32 v42, 0x3377d1cf, v40
	v_fmac_f32_e32 v42, 0x3f317217, v40
	v_cmp_lt_f32_e64 s[16:17], |v40|, s73
	s_nop 1
	v_cndmask_b32_e64 v40, v40, v42, s[16:17]
	v_cndmask_b32_e64 v42, 0, v128, s[0:1]
	v_sub_f32_e32 v40, v40, v42
	v_add_f32_e32 v40, v41, v40
	v_mul_f32_e32 v41, 0x3e000000, v44
	v_mul_f32_e64 v42, |v41|, s70
	v_exp_f32_e32 v42, v42
	s_or_b64 s[0:1], vcc, s[12:13]
	v_cndmask_b32_e64 v172, v129, v39, s[0:1]
	v_cndmask_b32_e64 v171, 0, -v40, s[0:1]
	v_add_f32_e32 v39, 1.0, v42
	v_cmp_gt_f32_e64 s[0:1], s71, v39
	v_add_f32_e32 v38, v171, v38
	s_nop 0
	v_cndmask_b32_e64 v40, 0, 32, s[0:1]
	v_ldexp_f32 v39, v39, v40
	v_log_f32_e32 v39, v39
	v_add_u32_e32 v40, 0x72, v0
	v_cmp_lt_u32_e64 s[12:13], v40, v130
	v_max_f32_e32 v40, 0, v41
	v_mul_f32_e32 v42, 0x3f317217, v39
	v_fma_f32 v42, v39, s72, -v42
	v_fmac_f32_e32 v42, 0x3377d1cf, v39
	v_fmac_f32_e32 v42, 0x3f317217, v39
	v_cmp_lt_f32_e64 s[16:17], |v39|, s73
	s_nop 1
	v_cndmask_b32_e64 v39, v39, v42, s[16:17]
	v_cndmask_b32_e64 v42, 0, v128, s[0:1]
	v_sub_f32_e32 v39, v39, v42
	v_add_f32_e32 v39, v40, v39
	v_mul_f32_e32 v40, 0x3e000000, v45
	v_mul_f32_e64 v42, |v40|, s70
	v_exp_f32_e32 v42, v42
	s_or_b64 s[0:1], vcc, s[12:13]
	v_cndmask_b32_e64 v173, 0, -v39, s[0:1]
	v_cndmask_b32_e64 v174, v129, v41, s[0:1]
	v_add_f32_e32 v39, 1.0, v42
	v_cmp_gt_f32_e64 s[0:1], s71, v39
	v_add_f32_e32 v38, v173, v38
	s_nop 0
	v_cndmask_b32_e64 v41, 0, 32, s[0:1]
	v_ldexp_f32 v39, v39, v41
	v_log_f32_e32 v39, v39
	v_add_u32_e32 v41, 0x73, v0
	v_cmp_lt_u32_e64 s[12:13], v41, v130
	v_max_f32_e32 v41, 0, v40
	v_mul_f32_e32 v42, 0x3f317217, v39
	v_fma_f32 v42, v39, s72, -v42
	v_fmac_f32_e32 v42, 0x3377d1cf, v39
	v_fmac_f32_e32 v42, 0x3f317217, v39
	v_cmp_lt_f32_e64 s[16:17], |v39|, s73
	s_nop 1
	v_cndmask_b32_e64 v39, v39, v42, s[16:17]
	v_cndmask_b32_e64 v42, 0, v128, s[0:1]
	v_sub_f32_e32 v39, v39, v42
	v_add_f32_e32 v39, v41, v39
	v_mul_f32_e32 v41, 0x3e000000, v46
	v_mul_f32_e64 v42, |v41|, s70
	v_exp_f32_e32 v42, v42
	s_or_b64 s[0:1], vcc, s[12:13]
	v_cndmask_b32_e64 v46, 0, -v39, s[0:1]
	v_add_f32_e32 v175, v46, v38
	v_add_f32_e32 v38, 1.0, v42
	v_cndmask_b32_e64 v176, v129, v40, s[0:1]
	v_cmp_gt_f32_e64 s[0:1], s71, v38
	s_nop 1
	v_cndmask_b32_e64 v39, 0, 32, s[0:1]
	v_ldexp_f32 v38, v38, v39
	v_log_f32_e32 v38, v38
	v_add_u32_e32 v39, 0x78, v0
	v_cmp_lt_u32_e64 s[12:13], v39, v130
	v_max_f32_e32 v39, 0, v41
	v_mul_f32_e32 v40, 0x3f317217, v38
	v_fma_f32 v40, v38, s72, -v40
	v_fmac_f32_e32 v40, 0x3377d1cf, v38
	v_fmac_f32_e32 v40, 0x3f317217, v38
	v_cmp_lt_f32_e64 s[16:17], |v38|, s73
	s_nop 1
	v_cndmask_b32_e64 v38, v38, v40, s[16:17]
	v_cndmask_b32_e64 v40, 0, v128, s[0:1]
	v_sub_f32_e32 v38, v38, v40
	v_add_f32_e32 v38, v39, v38
	v_mul_f32_e32 v39, 0x3e000000, v47
	v_mul_f32_e64 v40, |v39|, s70
	v_exp_f32_e32 v40, v40
	s_or_b64 s[0:1], vcc, s[12:13]
	v_cndmask_b32_e64 v177, 0, -v38, s[0:1]
	v_cndmask_b32_e64 v178, v129, v41, s[0:1]
	v_add_f32_e32 v40, 1.0, v40
	v_cmp_gt_f32_e64 s[0:1], s71, v40
	v_add_f32_e32 v38, 0, v177
	s_nop 0
	v_cndmask_b32_e64 v41, 0, 32, s[0:1]
	v_ldexp_f32 v40, v40, v41
	v_log_f32_e32 v40, v40
	v_add_u32_e32 v41, 0x79, v0
	v_cmp_lt_u32_e64 s[12:13], v41, v130
	v_max_f32_e32 v41, 0, v39
	v_mul_f32_e32 v42, 0x3f317217, v40
	v_fma_f32 v42, v40, s72, -v42
	v_fmac_f32_e32 v42, 0x3377d1cf, v40
	v_fmac_f32_e32 v42, 0x3f317217, v40
	v_cmp_lt_f32_e64 s[16:17], |v40|, s73
	s_nop 1
	v_cndmask_b32_e64 v40, v40, v42, s[16:17]
	v_cndmask_b32_e64 v42, 0, v128, s[0:1]
	v_sub_f32_e32 v40, v40, v42
	v_add_f32_e32 v40, v41, v40
	v_mul_f32_e32 v41, 0x3e000000, v48
	v_mul_f32_e64 v42, |v41|, s70
	v_exp_f32_e32 v42, v42
	s_or_b64 s[0:1], vcc, s[12:13]
	v_cndmask_b32_e64 v180, v129, v39, s[0:1]
	v_cndmask_b32_e64 v179, 0, -v40, s[0:1]
	v_add_f32_e32 v39, 1.0, v42
	v_cmp_gt_f32_e64 s[0:1], s71, v39
	v_add_f32_e32 v38, v179, v38
	s_nop 0
	v_cndmask_b32_e64 v40, 0, 32, s[0:1]
	v_ldexp_f32 v39, v39, v40
	v_log_f32_e32 v39, v39
	v_add_u32_e32 v40, 0x7a, v0
	v_cmp_lt_u32_e64 s[12:13], v40, v130
	v_max_f32_e32 v40, 0, v41
	v_mul_f32_e32 v42, 0x3f317217, v39
	v_fma_f32 v42, v39, s72, -v42
	v_fmac_f32_e32 v42, 0x3377d1cf, v39
	v_fmac_f32_e32 v42, 0x3f317217, v39
	v_cmp_lt_f32_e64 s[16:17], |v39|, s73
	v_add_u32_e32 v0, 0x7b, v0
	s_nop 0
	v_cndmask_b32_e64 v39, v39, v42, s[16:17]
	v_cndmask_b32_e64 v42, 0, v128, s[0:1]
	v_sub_f32_e32 v39, v39, v42
	v_add_f32_e32 v39, v40, v39
	v_mul_f32_e32 v40, 0x3e000000, v49
	v_mul_f32_e64 v42, |v40|, s70
	v_exp_f32_e32 v42, v42
	s_or_b64 s[0:1], vcc, s[12:13]
	v_cndmask_b32_e64 v181, 0, -v39, s[0:1]
	v_cndmask_b32_e64 v182, v129, v41, s[0:1]
	v_add_f32_e32 v39, 1.0, v42
	v_cmp_gt_f32_e64 s[0:1], s71, v39
	v_cmp_lt_u32_e64 s[12:13], v0, v130
	v_max_f32_e32 v0, 0, v40
	v_cndmask_b32_e64 v41, 0, 32, s[0:1]
	v_ldexp_f32 v39, v39, v41
	v_log_f32_e32 v39, v39
	s_or_b64 vcc, vcc, s[12:13]
	v_add_f32_e32 v38, v181, v38
	v_cndmask_b32_e32 v184, v129, v40, vcc
	v_mul_f32_e32 v41, 0x3f317217, v39
	v_fma_f32 v41, v39, s72, -v41
	v_fmac_f32_e32 v41, 0x3377d1cf, v39
	v_fmac_f32_e32 v41, 0x3f317217, v39
	v_cmp_lt_f32_e64 s[16:17], |v39|, s73
	s_nop 1
	v_cndmask_b32_e64 v39, v39, v41, s[16:17]
	v_cndmask_b32_e64 v41, 0, v128, s[0:1]
	v_sub_f32_e32 v39, v39, v41
	v_add_f32_e32 v0, v0, v39
	v_cndmask_b32_e64 v0, 0, -v0, vcc
	v_add_f32_e32 v183, v0, v38
	v_add_f32_e32 v47, v183, v175
	v_add_f32_e32 v48, v167, v47
	v_add_f32_e32 v49, v158, v48
	v_add_f32_e32 v38, v153, v49
	v_add_f32_e32 v39, v148, v38
	v_cmp_lt_i32_e32 vcc, v126, v127
	v_add_f32_e32 v40, v143, v39
	v_add_f32_e32 v185, v138, v40
	v_cndmask_b32_e32 v41, v125, v126, vcc
	v_lshlrev_b32_e32 v41, 2, v41
	ds_bpermute_b32 v186, v41, v185
	ds_bpermute_b32 v42, v41, v40
	ds_bpermute_b32 v43, v41, v39
	ds_bpermute_b32 v44, v41, v38
	ds_bpermute_b32 v187, v41, v49
	ds_bpermute_b32 v188, v41, v48
	ds_bpermute_b32 v189, v41, v47
	ds_bpermute_b32 v190, v41, v183
	v_sub_f32_e32 v41, v185, v138
	s_waitcnt lgkmcnt(0)
	v_cndmask_b32_e64 v45, v42, v186, s[8:9]
	v_add_f32_e32 v41, v45, v41
	v_sub_f32_e32 v40, v40, v143
	v_cndmask_b32_e64 v42, v43, v42, s[8:9]
	v_sub_f32_e32 v39, v39, v148
	v_cndmask_b32_e64 v43, v44, v43, s[8:9]
	v_add_f32_e32 v41, v131, v41
	v_add_f32_e32 v40, v42, v40
	v_add_f32_e32 v39, v43, v39
	v_add_f32_e32 v41, v54, v41
	v_add_f32_e32 v40, v131, v40
	v_add_f32_e32 v39, v131, v39
	v_add_f32_e32 v45, v136, v41
	v_add_f32_e32 v41, v53, v41
	v_add_f32_e32 v40, v58, v40
	v_add_f32_e32 v39, v62, v39
	v_add_f32_e32 v53, v135, v41
	v_add_f32_e32 v41, v52, v41
	v_add_f32_e32 v42, v141, v40
	v_add_f32_e32 v40, v57, v40
	v_add_f32_e32 v43, v146, v39
	v_add_f32_e32 v39, v61, v39
	v_add_f32_e32 v52, v134, v41
	v_add_f32_e32 v41, v50, v41
	v_add_f32_e32 v50, v140, v40
	v_add_f32_e32 v40, v56, v40
	v_add_f32_e32 v54, v145, v39
	v_add_f32_e32 v39, v60, v39
	v_add_f32_e32 v41, v51, v41
	v_add_f32_e32 v51, v139, v40
	v_add_f32_e32 v40, v55, v40
	v_add_f32_e32 v55, v144, v39
	v_add_f32_e32 v39, v59, v39
	v_add_f32_e32 v39, v142, v39
	v_mul_f32_e32 v39, 0x3fb8aa3b, v39
	v_exp_f32_e32 v56, v39
	v_sub_f32_e32 v38, v38, v153
	v_cndmask_b32_e64 v39, v187, v44, s[8:9]
	v_add_f32_e32 v38, v39, v38
	v_add_f32_e32 v38, v131, v38
	v_add_f32_e32 v38, v151, v38
	v_add_f32_e32 v39, v152, v38
	v_mul_f32_e32 v39, 0x3fb8aa3b, v39
	v_add_f32_e32 v38, v65, v38
	v_mul_f32_e32 v52, 0x3fb8aa3b, v52
	v_mul_f32_e32 v41, 0x3fb8aa3b, v41
	v_mul_f32_e32 v42, 0x3fb8aa3b, v42
	v_mul_f32_e32 v50, 0x3fb8aa3b, v50
	v_exp_f32_e32 v57, v39
	v_add_f32_e32 v39, v150, v38
	v_exp_f32_e32 v52, v52
	v_exp_f32_e32 v41, v41
	v_exp_f32_e32 v42, v42
	v_exp_f32_e32 v50, v50
	v_mul_f32_e32 v39, 0x3fb8aa3b, v39
	v_add_f32_e32 v38, v64, v38
	v_exp_f32_e32 v58, v39
	v_add_f32_e32 v39, v149, v38
	v_add_f32_e32 v38, v63, v38
	v_add_f32_e32 v38, v147, v38
	v_mul_f32_e32 v38, 0x3fb8aa3b, v38
	v_exp_f32_e32 v59, v38
	v_cvt_pk_bf16_f32 v38, v41, v52
	v_cvt_pk_bf16_f32 v41, v50, v42
	v_sub_f32_e32 v49, v49, v158
	v_cndmask_b32_e64 v50, v188, v187, s[8:9]
	v_add_f32_e32 v49, v50, v49
	v_add_f32_e32 v49, v131, v49
	v_add_f32_e32 v49, v157, v49
	v_mul_f32_e32 v45, 0x3fb8aa3b, v45
	v_mul_f32_e32 v53, 0x3fb8aa3b, v53
	v_add_f32_e32 v37, v37, v49
	v_exp_f32_e32 v45, v45
	v_exp_f32_e32 v53, v53
	v_add_f32_e32 v36, v36, v37
	v_add_f32_e32 v34, v34, v36
	v_add_f32_e32 v34, v35, v34
	v_mul_f32_e32 v39, 0x3fb8aa3b, v39
	v_mul_f32_e32 v34, 0x3fb8aa3b, v34
	v_exp_f32_e32 v44, v39
	v_cvt_pk_bf16_f32 v39, v53, v45
	v_cvt_pk_bf16_f32 v45, v58, v57
	v_exp_f32_e32 v57, v34
	v_sub_f32_e32 v34, v48, v167
	v_cndmask_b32_e64 v35, v189, v188, s[8:9]
	v_add_f32_e32 v34, v35, v34
	v_add_f32_e32 v34, v131, v34
	v_add_f32_e32 v34, v161, v34
	v_add_f32_e32 v35, v168, v34
	v_mul_f32_e32 v35, 0x3fb8aa3b, v35
	v_add_f32_e32 v34, v165, v34
	v_exp_f32_e32 v58, v35
	v_add_f32_e32 v35, v166, v34
	v_mul_f32_e32 v35, 0x3fb8aa3b, v35
	v_add_f32_e32 v34, v164, v34
	v_cvt_pk_bf16_f32 v44, v59, v44
	v_exp_f32_e32 v59, v35
	v_add_f32_e32 v35, v162, v34
	v_add_f32_e32 v34, v160, v34
	v_add_f32_e32 v34, v163, v34
	v_mul_f32_e32 v35, 0x3fb8aa3b, v35
	v_mul_f32_e32 v34, 0x3fb8aa3b, v34
	v_exp_f32_e32 v60, v35
	v_exp_f32_e32 v61, v34
	v_sub_f32_e32 v34, v47, v175
	v_cndmask_b32_e64 v35, v190, v189, s[8:9]
	v_add_f32_e32 v34, v35, v34
	v_add_f32_e32 v34, v131, v34
	v_add_f32_e32 v34, v46, v34
	v_mul_f32_e32 v55, 0x3fb8aa3b, v55
	v_add_f32_e32 v35, v176, v34
	v_add_f32_e32 v40, v137, v40
	v_exp_f32_e32 v55, v55
	v_mul_f32_e32 v35, 0x3fb8aa3b, v35
	v_add_f32_e32 v34, v173, v34
	v_mul_f32_e32 v51, 0x3fb8aa3b, v51
	v_mul_f32_e32 v40, 0x3fb8aa3b, v40
	v_mul_f32_e32 v43, 0x3fb8aa3b, v43
	v_mul_f32_e32 v54, 0x3fb8aa3b, v54
	v_exp_f32_e32 v62, v35
	v_add_f32_e32 v35, v174, v34
	v_add_f32_e32 v64, v171, v34
	v_add3_u32 v34, s81, v110, v111
	v_exp_f32_e32 v51, v51
	v_exp_f32_e32 v40, v40
	v_exp_f32_e32 v43, v43
	v_exp_f32_e32 v54, v54
	v_add_f32_e32 v50, v159, v49
	v_add_f32_e32 v49, v156, v37
	v_add_f32_e32 v37, v155, v36
	v_add3_u32 v46, v34, v119, v120
	v_mul_f32_e32 v37, 0x3fb8aa3b, v37
	v_mul_f32_e32 v35, 0x3fb8aa3b, v35
	v_add_u32_e32 v65, v46, v118
	v_cvt_pk_bf16_f32 v42, v56, v55
	v_exp_f32_e32 v56, v37
	v_exp_f32_e32 v63, v35
	ds_read_b64_tr_b16 v[34:35], v65 offset:8192
	ds_read_b64_tr_b16 v[36:37], v65 offset:9216
	v_add_f32_e32 v47, v172, v64
	v_mul_f32_e32 v50, 0x3fb8aa3b, v50
	v_mul_f32_e32 v49, 0x3fb8aa3b, v49
	v_mul_f32_e32 v47, 0x3fb8aa3b, v47
	v_add_u32_e32 v135, v46, v121
	v_cvt_pk_bf16_f32 v40, v40, v51
	v_cvt_pk_bf16_f32 v43, v54, v43
	v_exp_f32_e32 v54, v50
	v_exp_f32_e32 v55, v49
	v_exp_f32_e32 v134, v47
	ds_read_b64_tr_b16 v[46:47], v135 offset:8192
	ds_read_b64_tr_b16 v[48:49], v135 offset:9216
	ds_read_b64_tr_b16 v[50:51], v65 offset:10240
	ds_read_b64_tr_b16 v[52:53], v65 offset:11264
	s_waitcnt lgkmcnt(4)
	v_mfma_f32_32x32x16_bf16 v[18:33], v[34:37], v[38:41], v[18:33]
	v_add_f32_e32 v34, v169, v64
	v_add_f32_e32 v34, v170, v34
	v_mul_f32_e32 v34, 0x3fb8aa3b, v34
	v_exp_f32_e32 v64, v34
	ds_read_b64_tr_b16 v[34:35], v135 offset:10240
	ds_read_b64_tr_b16 v[36:37], v135 offset:11264
	v_sub_f32_e32 v136, v183, v183
	s_waitcnt lgkmcnt(4)
	v_mfma_f32_32x32x16_bf16 v[2:17], v[46:49], v[38:41], v[2:17]
	v_cndmask_b32_e64 v38, 0, v190, s[8:9]
	v_add_f32_e32 v38, v38, v136
	v_add_f32_e32 v38, v131, v38
	v_add_f32_e32 v0, v0, v38
	ds_read_b64_tr_b16 v[46:47], v65 offset:12288
	ds_read_b64_tr_b16 v[48:49], v65 offset:13312
	v_add_f32_e32 v38, v184, v0
	v_mul_f32_e32 v38, 0x3fb8aa3b, v38
	s_waitcnt lgkmcnt(4)
	v_mfma_f32_32x32x16_bf16 v[18:33], v[50:53], v[42:45], v[18:33]
	v_add_f32_e32 v0, v181, v0
	v_exp_f32_e32 v136, v38
	v_add_f32_e32 v38, v182, v0
	v_mul_f32_e32 v50, 0x3fb8aa3b, v38
	v_add_f32_e32 v0, v179, v0
	v_cvt_pk_bf16_f32 v38, v57, v56
	v_cvt_pk_bf16_f32 v39, v55, v54
	s_waitcnt lgkmcnt(2)
	v_mfma_f32_32x32x16_bf16 v[2:17], v[34:37], v[42:45], v[2:17]
	ds_read_b64_tr_b16 v[34:35], v135 offset:12288
	ds_read_b64_tr_b16 v[36:37], v135 offset:13312
	ds_read_b64_tr_b16 v[42:43], v65 offset:14336
	ds_read_b64_tr_b16 v[44:45], v65 offset:15360
	v_cvt_pk_bf16_f32 v40, v61, v60
	v_cvt_pk_bf16_f32 v41, v59, v58
	s_waitcnt lgkmcnt(4)
	s_nop 0
	v_mfma_f32_32x32x16_bf16 v[18:33], v[46:49], v[38:41], v[18:33]
	v_add_f32_e32 v46, v180, v0
	v_add_f32_e32 v0, v177, v0
	v_add_f32_e32 v0, v178, v0
	v_mul_f32_e32 v46, 0x3fb8aa3b, v46
	v_mul_f32_e32 v0, 0x3fb8aa3b, v0
	v_exp_f32_e32 v51, v46
	ds_read_b64_tr_b16 v[46:47], v135 offset:14336
	ds_read_b64_tr_b16 v[48:49], v135 offset:15360
	s_waitcnt lgkmcnt(4)
	v_mfma_f32_32x32x16_bf16 v[2:17], v[34:37], v[38:41], v[2:17]
	v_exp_f32_e32 v0, v0
	v_exp_f32_e32 v37, v50
	v_cvt_pk_bf16_f32 v34, v64, v134
	v_cvt_pk_bf16_f32 v35, v63, v62
	v_cvt_pk_bf16_f32 v36, v0, v51
	v_cvt_pk_bf16_f32 v37, v37, v136
	v_add_f32_e32 v0, v185, v186
	v_add_f32_e32 v131, v131, v0
	s_waitcnt lgkmcnt(2)
	v_mfma_f32_32x32x16_bf16 v[18:33], v[42:45], v[34:37], v[18:33]
	s_waitcnt lgkmcnt(0)
	v_mfma_f32_32x32x16_bf16 v[2:17], v[46:49], v[34:37], v[2:17]
